# top-k scatter: the per-chunk output bases are read from LDS once up front instead of once per chunk
# baseline (speedup 1.0000x reference)
; DI void topk_job(const Params& p, int b, int t0, char* lds) {
;     ...
;     if (lane == 0) ng[q] = cg_;
;   }
;   __syncthreads();
;   const unsigned long long lt = (1ull << lane) - 1ull;
; #pragma unroll
;   for (int i = 0; i < 17; ++i) {
;     const int c = 1 + w + 8 * i;
;     if (c <= cmax) {
;       const int key = c * 64 + lane;
; #pragma unroll
;       for (int q = 0; q < 4; ++q) {
;         u16* out = p.IDX + (size_t)(b * PP + t0 + q) * 256;
;         const bool gt = sc[i][q] > T[q];
;         const bool eq = (sc[i][q] == T[q]) && (T[q] != 0u);
;         const unsigned long long m1 = __ballot(gt), m2 = __ballot(eq);
;         if ((m1 | m2) != 0ull) {
;           const unsigned bb = baseb[q * 132 + c];
;           if (gt) out[(int)(bb & 0xffffu) + __popcll(m1 & lt)] = (u16)key;
;           if (eq) { const int pos = ng[q] + (int)(bb >> 16) + __popcll(m2 & lt); if (pos < 256) out[pos] = (u16)key; }
;         }
;       }
;     }
;   }
.Ltk_pfx_end_90:
	s_waitcnt lgkmcnt(0)
	s_barrier
	ds_read_b128 v[4:7], v3 offset:256
	s_movk_i32 s84, 0x100
	s_waitcnt lgkmcnt(0)
	v_readfirstlane_b32 s48, v4
	v_readfirstlane_b32 s49, v5
	v_readfirstlane_b32 s50, v6
	v_readfirstlane_b32 s51, v7
	s_add_i32 s28, s2, 1
	s_cmp_gt_u32 s28, s3
	s_cbranch_scc1 .Ltk_rdb_done_92
	s_lshl_b32 s29, s28, 2
	s_addk_i32 s29, 0x1000
	v_mov_b32_e32 v11, s29
	ds_read_b32 v20, v11
	ds_read_b32 v21, v11 offset:544
	ds_read_b32 v22, v11 offset:1088
	ds_read_b32 v23, v11 offset:1632
	s_add_i32 s28, s28, 8
	s_cmp_gt_u32 s28, s3
	s_cbranch_scc1 .Ltk_rdb_done_92
	s_lshl_b32 s29, s28, 2
	s_addk_i32 s29, 0x1000
	v_mov_b32_e32 v11, s29
	ds_read_b32 v24, v11
	ds_read_b32 v25, v11 offset:544
	ds_read_b32 v26, v11 offset:1088
	ds_read_b32 v27, v11 offset:1632
	s_add_i32 s28, s28, 8
	s_cmp_gt_u32 s28, s3
	s_cbranch_scc1 .Ltk_rdb_done_92
	s_lshl_b32 s29, s28, 2
	s_addk_i32 s29, 0x1000
	v_mov_b32_e32 v11, s29
	ds_read_b32 v28, v11
	ds_read_b32 v29, v11 offset:544
	ds_read_b32 v30, v11 offset:1088
	ds_read_b32 v31, v11 offset:1632
	s_add_i32 s28, s28, 8
	s_cmp_gt_u32 s28, s3
	s_cbranch_scc1 .Ltk_rdb_done_92
	s_lshl_b32 s29, s28, 2
	s_addk_i32 s29, 0x1000
	v_mov_b32_e32 v11, s29
	ds_read_b32 v32, v11
	ds_read_b32 v33, v11 offset:544
	ds_read_b32 v34, v11 offset:1088
	ds_read_b32 v35, v11 offset:1632
	s_add_i32 s28, s28, 8
	s_cmp_gt_u32 s28, s3
	s_cbranch_scc1 .Ltk_rdb_done_92
	s_lshl_b32 s29, s28, 2
	s_addk_i32 s29, 0x1000
	v_mov_b32_e32 v11, s29
	ds_read_b32 v36, v11
	ds_read_b32 v37, v11 offset:544
	ds_read_b32 v38, v11 offset:1088
	ds_read_b32 v39, v11 offset:1632
	s_add_i32 s28, s28, 8
	s_cmp_gt_u32 s28, s3
	s_cbranch_scc1 .Ltk_rdb_done_92
	s_lshl_b32 s29, s28, 2
	s_addk_i32 s29, 0x1000
	v_mov_b32_e32 v11, s29
	ds_read_b32 v40, v11
	ds_read_b32 v41, v11 offset:544
	ds_read_b32 v42, v11 offset:1088
	ds_read_b32 v43, v11 offset:1632
	s_add_i32 s28, s28, 8
	s_cmp_gt_u32 s28, s3
	s_cbranch_scc1 .Ltk_rdb_done_92
	s_lshl_b32 s29, s28, 2
	s_addk_i32 s29, 0x1000
	v_mov_b32_e32 v11, s29
	ds_read_b32 v44, v11
	ds_read_b32 v45, v11 offset:544
	ds_read_b32 v46, v11 offset:1088
	ds_read_b32 v47, v11 offset:1632
	s_add_i32 s28, s28, 8
	s_cmp_gt_u32 s28, s3
	s_cbranch_scc1 .Ltk_rdb_done_92
	s_lshl_b32 s29, s28, 2
	s_addk_i32 s29, 0x1000
	v_mov_b32_e32 v11, s29
	ds_read_b32 v48, v11
	ds_read_b32 v49, v11 offset:544
	ds_read_b32 v50, v11 offset:1088
	ds_read_b32 v51, v11 offset:1632
	s_add_i32 s28, s28, 8
	s_cmp_gt_u32 s28, s3
	s_cbranch_scc1 .Ltk_rdb_done_92
	s_lshl_b32 s29, s28, 2
	s_addk_i32 s29, 0x1000
	v_mov_b32_e32 v11, s29
	ds_read_b32 v52, v11
	ds_read_b32 v53, v11 offset:544
	ds_read_b32 v54, v11 offset:1088
	ds_read_b32 v55, v11 offset:1632
	s_add_i32 s28, s28, 8
	s_cmp_gt_u32 s28, s3
	s_cbranch_scc1 .Ltk_rdb_done_92
	s_lshl_b32 s29, s28, 2
	s_addk_i32 s29, 0x1000
	v_mov_b32_e32 v11, s29
	ds_read_b32 v56, v11
	ds_read_b32 v57, v11 offset:544
	ds_read_b32 v58, v11 offset:1088
	ds_read_b32 v59, v11 offset:1632
	s_add_i32 s28, s28, 8
	s_cmp_gt_u32 s28, s3
	s_cbranch_scc1 .Ltk_rdb_done_92
	s_lshl_b32 s29, s28, 2
	s_addk_i32 s29, 0x1000
	v_mov_b32_e32 v11, s29
	ds_read_b32 v60, v11
	ds_read_b32 v61, v11 offset:544
	ds_read_b32 v62, v11 offset:1088
	ds_read_b32 v63, v11 offset:1632
	s_add_i32 s28, s28, 8
	s_cmp_gt_u32 s28, s3
	s_cbranch_scc1 .Ltk_rdb_done_92
	s_lshl_b32 s29, s28, 2
	s_addk_i32 s29, 0x1000
	v_mov_b32_e32 v11, s29
	ds_read_b32 v64, v11
	ds_read_b32 v65, v11 offset:544
	ds_read_b32 v66, v11 offset:1088
	ds_read_b32 v77, v11 offset:1632
	s_add_i32 s28, s28, 8
	s_cmp_gt_u32 s28, s3
	s_cbranch_scc1 .Ltk_rdb_done_92
	s_lshl_b32 s29, s28, 2
	s_addk_i32 s29, 0x1000
	v_mov_b32_e32 v11, s29
	ds_read_b32 v78, v11
	ds_read_b32 v79, v11 offset:544
	ds_read_b32 v80, v11 offset:1088
	ds_read_b32 v81, v11 offset:1632
	s_add_i32 s28, s28, 8
	s_cmp_gt_u32 s28, s3
	s_cbranch_scc1 .Ltk_rdb_done_92
	s_lshl_b32 s29, s28, 2
	s_addk_i32 s29, 0x1000
	v_mov_b32_e32 v11, s29
	ds_read_b32 v82, v11
	ds_read_b32 v83, v11 offset:544
	ds_read_b32 v120, v11 offset:1088
	ds_read_b32 v122, v11 offset:1632
	s_add_i32 s28, s28, 8
	s_cmp_gt_u32 s28, s3
	s_cbranch_scc1 .Ltk_rdb_done_92
	s_lshl_b32 s29, s28, 2
	s_addk_i32 s29, 0x1000
	v_mov_b32_e32 v11, s29
	ds_read_b32 v124, v11
	ds_read_b32 v126, v11 offset:544
	ds_read_b32 v128, v11 offset:1088
	ds_read_b32 v130, v11 offset:1632
	s_add_i32 s28, s28, 8
	s_cmp_gt_u32 s28, s3
	s_cbranch_scc1 .Ltk_rdb_done_92
	s_lshl_b32 s29, s28, 2
	s_addk_i32 s29, 0x1000
	v_mov_b32_e32 v11, s29
	ds_read_b32 v132, v11
	ds_read_b32 v134, v11 offset:544
	ds_read_b32 v137, v11 offset:1088
	ds_read_b32 v209, v11 offset:1632
	s_add_i32 s28, s28, 8
	s_cmp_gt_u32 s28, s3
	s_cbranch_scc1 .Ltk_rdb_done_92
	s_lshl_b32 s29, s28, 2
	s_addk_i32 s29, 0x1000
	v_mov_b32_e32 v11, s29
	ds_read_b32 v210, v11
	ds_read_b32 v228, v11 offset:544
	ds_read_b32 v229, v11 offset:1088
	ds_read_b32 v230, v11 offset:1632
.Ltk_rdb_done_92:
	s_waitcnt lgkmcnt(0)
	s_add_i32 s28, s2, 1
	s_cmp_gt_u32 s28, s3
	s_cbranch_scc1 .Ltk_scat_done_93
	v_lshl_add_u32 v6, s28, 6, v101
	v_cmp_lt_u32_e64 s[68:69], s12, v208
	v_cmp_eq_u32_e32 vcc, s12, v208
	v_and_b32_e32 v0, 0xffff, v20
	v_mbcnt_lo_u32_b32 v7, s68, 0
	v_mbcnt_hi_u32_b32 v7, s69, v7
	v_add_lshl_u32 v0, v0, v7, 1
	v_cndmask_b32_e64 v0, v76, v0, s[68:69]
	ds_write_b16 v0, v6 offset:8192
	s_cbranch_vccz .Ltk_noeq_94
	s_cmp_eq_u32 s12, 0
	s_cbranch_scc1 .Ltk_noeq_94
	v_mbcnt_lo_u32_b32 v8, vcc_lo, 0
	v_mbcnt_hi_u32_b32 v8, vcc_hi, v8
	v_lshrrev_b32_e32 v1, 16, v20
	v_add3_u32 v1, v1, v8, s48
	v_cmp_gt_u32_e64 s[72:73], s84, v1
	v_lshlrev_b32_e32 v1, 1, v1
	s_and_b64 s[72:73], s[72:73], vcc
	s_nop 0
	v_cndmask_b32_e64 v1, v76, v1, s[72:73]
	ds_write_b16 v1, v6 offset:8192
; DI void topk_job(const Params& p, int b, int t0, char* lds) {
;     ...
;   const unsigned long long lt = (1ull << lane) - 1ull;
; #pragma unroll
;   for (int i = 0; i < 17; ++i) {
;     const int c = 1 + w + 8 * i;
;     if (c <= cmax) {
;       const int key = c * 64 + lane;
; #pragma unroll
;       for (int q = 0; q < 4; ++q) {
;         u16* out = p.IDX + (size_t)(b * PP + t0 + q) * 256;
;         const bool gt = sc[i][q] > T[q];
;         const bool eq = (sc[i][q] == T[q]) && (T[q] != 0u);
;         const unsigned long long m1 = __ballot(gt), m2 = __ballot(eq);
;         if ((m1 | m2) != 0ull) {
;           const unsigned bb = baseb[q * 132 + c];
;           if (gt) out[(int)(bb & 0xffffu) + __popcll(m1 & lt)] = (u16)key;
;           if (eq) { const int pos = ng[q] + (int)(bb >> 16) + __popcll(m2 & lt); if (pos < 256) out[pos] = (u16)key; }
;         }
;       }
;     }
;   }
.Ltk_noeq_94:
	v_cmp_lt_u32_e64 s[68:69], s13, v175
	v_cmp_eq_u32_e32 vcc, s13, v175
	v_and_b32_e32 v0, 0xffff, v21
	v_mbcnt_lo_u32_b32 v7, s68, 0
	v_mbcnt_hi_u32_b32 v7, s69, v7
	v_add_lshl_u32 v0, v0, v7, 1
	v_cndmask_b32_e64 v0, v76, v0, s[68:69]
	ds_write_b16 v0, v6 offset:8704
	s_cbranch_vccz .Ltk_noeq_95
	s_cmp_eq_u32 s13, 0
	s_cbranch_scc1 .Ltk_noeq_95
	v_mbcnt_lo_u32_b32 v8, vcc_lo, 0
	v_mbcnt_hi_u32_b32 v8, vcc_hi, v8
	v_lshrrev_b32_e32 v1, 16, v21
	v_add3_u32 v1, v1, v8, s49
	v_cmp_gt_u32_e64 s[72:73], s84, v1
	v_lshlrev_b32_e32 v1, 1, v1
	s_and_b64 s[72:73], s[72:73], vcc
	s_nop 0
	v_cndmask_b32_e64 v1, v76, v1, s[72:73]
	ds_write_b16 v1, v6 offset:8704
.Ltk_noeq_95:
	v_cmp_lt_u32_e64 s[68:69], s14, v161
	v_cmp_eq_u32_e32 vcc, s14, v161
	v_and_b32_e32 v0, 0xffff, v22
	v_mbcnt_lo_u32_b32 v7, s68, 0
	v_mbcnt_hi_u32_b32 v7, s69, v7
	v_add_lshl_u32 v0, v0, v7, 1
	v_cndmask_b32_e64 v0, v76, v0, s[68:69]
	ds_write_b16 v0, v6 offset:9216
	s_cbranch_vccz .Ltk_noeq_96
	s_cmp_eq_u32 s14, 0
	s_cbranch_scc1 .Ltk_noeq_96
	v_mbcnt_lo_u32_b32 v8, vcc_lo, 0
	v_mbcnt_hi_u32_b32 v8, vcc_hi, v8
	v_lshrrev_b32_e32 v1, 16, v22
	v_add3_u32 v1, v1, v8, s50
	v_cmp_gt_u32_e64 s[72:73], s84, v1
	v_lshlrev_b32_e32 v1, 1, v1
	s_and_b64 s[72:73], s[72:73], vcc
	s_nop 0
	v_cndmask_b32_e64 v1, v76, v1, s[72:73]
	ds_write_b16 v1, v6 offset:9216
.Ltk_noeq_96:
	v_cmp_lt_u32_e64 s[68:69], s15, v138
	v_cmp_eq_u32_e32 vcc, s15, v138
	v_and_b32_e32 v0, 0xffff, v23
	v_mbcnt_lo_u32_b32 v7, s68, 0
	v_mbcnt_hi_u32_b32 v7, s69, v7
	v_add_lshl_u32 v0, v0, v7, 1
	v_cndmask_b32_e64 v0, v76, v0, s[68:69]
	ds_write_b16 v0, v6 offset:9728
	s_cbranch_vccz .Ltk_noeq_97
	s_cmp_eq_u32 s15, 0
	s_cbranch_scc1 .Ltk_noeq_97
	v_mbcnt_lo_u32_b32 v8, vcc_lo, 0
	v_mbcnt_hi_u32_b32 v8, vcc_hi, v8
	v_lshrrev_b32_e32 v1, 16, v23
	v_add3_u32 v1, v1, v8, s51
	v_cmp_gt_u32_e64 s[72:73], s84, v1
	v_lshlrev_b32_e32 v1, 1, v1
	s_and_b64 s[72:73], s[72:73], vcc
	s_nop 0
	v_cndmask_b32_e64 v1, v76, v1, s[72:73]
	ds_write_b16 v1, v6 offset:9728
.Ltk_noeq_97:
	s_add_i32 s28, s28, 8
	s_cmp_gt_u32 s28, s3
	s_cbranch_scc1 .Ltk_scat_done_93
	v_lshl_add_u32 v6, s28, 6, v101
	v_cmp_lt_u32_e64 s[68:69], s12, v207
	v_cmp_eq_u32_e32 vcc, s12, v207
	v_and_b32_e32 v0, 0xffff, v24
	v_mbcnt_lo_u32_b32 v7, s68, 0
	v_mbcnt_hi_u32_b32 v7, s69, v7
	v_add_lshl_u32 v0, v0, v7, 1
	v_cndmask_b32_e64 v0, v76, v0, s[68:69]
	ds_write_b16 v0, v6 offset:8192
	s_cbranch_vccz .Ltk_noeq_98
	s_cmp_eq_u32 s12, 0
	s_cbranch_scc1 .Ltk_noeq_98
	v_mbcnt_lo_u32_b32 v8, vcc_lo, 0
	v_mbcnt_hi_u32_b32 v8, vcc_hi, v8
	v_lshrrev_b32_e32 v1, 16, v24
	v_add3_u32 v1, v1, v8, s48
	v_cmp_gt_u32_e64 s[72:73], s84, v1
	v_lshlrev_b32_e32 v1, 1, v1
	s_and_b64 s[72:73], s[72:73], vcc
	s_nop 0
	v_cndmask_b32_e64 v1, v76, v1, s[72:73]
	ds_write_b16 v1, v6 offset:8192
.Ltk_noeq_98:
	v_cmp_lt_u32_e64 s[68:69], s13, v173
	v_cmp_eq_u32_e32 vcc, s13, v173
	v_and_b32_e32 v0, 0xffff, v25
	v_mbcnt_lo_u32_b32 v7, s68, 0
	v_mbcnt_hi_u32_b32 v7, s69, v7
	v_add_lshl_u32 v0, v0, v7, 1
	v_cndmask_b32_e64 v0, v76, v0, s[68:69]
	ds_write_b16 v0, v6 offset:8704
	s_cbranch_vccz .Ltk_noeq_99
	s_cmp_eq_u32 s13, 0
	s_cbranch_scc1 .Ltk_noeq_99
	v_mbcnt_lo_u32_b32 v8, vcc_lo, 0
	v_mbcnt_hi_u32_b32 v8, vcc_hi, v8
	v_lshrrev_b32_e32 v1, 16, v25
	v_add3_u32 v1, v1, v8, s49
	v_cmp_gt_u32_e64 s[72:73], s84, v1
	v_lshlrev_b32_e32 v1, 1, v1
	s_and_b64 s[72:73], s[72:73], vcc
	s_nop 0
	v_cndmask_b32_e64 v1, v76, v1, s[72:73]
	ds_write_b16 v1, v6 offset:8704
.Ltk_noeq_99:
	v_cmp_lt_u32_e64 s[68:69], s14, v159
	v_cmp_eq_u32_e32 vcc, s14, v159
	v_and_b32_e32 v0, 0xffff, v26
	v_mbcnt_lo_u32_b32 v7, s68, 0
	v_mbcnt_hi_u32_b32 v7, s69, v7
	v_add_lshl_u32 v0, v0, v7, 1
	v_cndmask_b32_e64 v0, v76, v0, s[68:69]
	ds_write_b16 v0, v6 offset:9216
	s_cbranch_vccz .Ltk_noeq_100
	s_cmp_eq_u32 s14, 0
	s_cbranch_scc1 .Ltk_noeq_100
	v_mbcnt_lo_u32_b32 v8, vcc_lo, 0
	v_mbcnt_hi_u32_b32 v8, vcc_hi, v8
	v_lshrrev_b32_e32 v1, 16, v26
	v_add3_u32 v1, v1, v8, s50
	v_cmp_gt_u32_e64 s[72:73], s84, v1
	v_lshlrev_b32_e32 v1, 1, v1
	s_and_b64 s[72:73], s[72:73], vcc
	s_nop 0
	v_cndmask_b32_e64 v1, v76, v1, s[72:73]
	ds_write_b16 v1, v6 offset:9216
.Ltk_noeq_100:
	v_cmp_lt_u32_e64 s[68:69], s15, v135
	v_cmp_eq_u32_e32 vcc, s15, v135
	v_and_b32_e32 v0, 0xffff, v27
	v_mbcnt_lo_u32_b32 v7, s68, 0
	v_mbcnt_hi_u32_b32 v7, s69, v7
	v_add_lshl_u32 v0, v0, v7, 1
	v_cndmask_b32_e64 v0, v76, v0, s[68:69]
	ds_write_b16 v0, v6 offset:9728
	s_cbranch_vccz .Ltk_noeq_101
	s_cmp_eq_u32 s15, 0
	s_cbranch_scc1 .Ltk_noeq_101
	v_mbcnt_lo_u32_b32 v8, vcc_lo, 0
	v_mbcnt_hi_u32_b32 v8, vcc_hi, v8
	v_lshrrev_b32_e32 v1, 16, v27
	v_add3_u32 v1, v1, v8, s51
	v_cmp_gt_u32_e64 s[72:73], s84, v1
	v_lshlrev_b32_e32 v1, 1, v1
	s_and_b64 s[72:73], s[72:73], vcc
	s_nop 0
	v_cndmask_b32_e64 v1, v76, v1, s[72:73]
	ds_write_b16 v1, v6 offset:9728
.Ltk_noeq_101:
	s_add_i32 s28, s28, 8
	s_cmp_gt_u32 s28, s3
	s_cbranch_scc1 .Ltk_scat_done_93
	v_lshl_add_u32 v6, s28, 6, v101
	v_cmp_lt_u32_e64 s[68:69], s12, v187
	v_cmp_eq_u32_e32 vcc, s12, v187
	v_and_b32_e32 v0, 0xffff, v28
	v_mbcnt_lo_u32_b32 v7, s68, 0
	v_mbcnt_hi_u32_b32 v7, s69, v7
	v_add_lshl_u32 v0, v0, v7, 1
	v_cndmask_b32_e64 v0, v76, v0, s[68:69]
	ds_write_b16 v0, v6 offset:8192
	s_cbranch_vccz .Ltk_noeq_102
	s_cmp_eq_u32 s12, 0
	s_cbranch_scc1 .Ltk_noeq_102
	v_mbcnt_lo_u32_b32 v8, vcc_lo, 0
	v_mbcnt_hi_u32_b32 v8, vcc_hi, v8
	v_lshrrev_b32_e32 v1, 16, v28
	v_add3_u32 v1, v1, v8, s48
	v_cmp_gt_u32_e64 s[72:73], s84, v1
	v_lshlrev_b32_e32 v1, 1, v1
	s_and_b64 s[72:73], s[72:73], vcc
	s_nop 0
	v_cndmask_b32_e64 v1, v76, v1, s[72:73]
	ds_write_b16 v1, v6 offset:8192
; DI void topk_job(const Params& p, int b, int t0, char* lds) {
;     ...
;   const unsigned long long lt = (1ull << lane) - 1ull;
; #pragma unroll
;   for (int i = 0; i < 17; ++i) {
;     const int c = 1 + w + 8 * i;
;     if (c <= cmax) {
;       const int key = c * 64 + lane;
; #pragma unroll
;       for (int q = 0; q < 4; ++q) {
;         u16* out = p.IDX + (size_t)(b * PP + t0 + q) * 256;
;         const bool gt = sc[i][q] > T[q];
;         const bool eq = (sc[i][q] == T[q]) && (T[q] != 0u);
;         const unsigned long long m1 = __ballot(gt), m2 = __ballot(eq);
;         if ((m1 | m2) != 0ull) {
;           const unsigned bb = baseb[q * 132 + c];
;           if (gt) out[(int)(bb & 0xffffu) + __popcll(m1 & lt)] = (u16)key;
;           if (eq) { const int pos = ng[q] + (int)(bb >> 16) + __popcll(m2 & lt); if (pos < 256) out[pos] = (u16)key; }
;         }
;       }
;     }
;   }
.Ltk_noeq_102:
	v_cmp_lt_u32_e64 s[68:69], s13, v172
	v_cmp_eq_u32_e32 vcc, s13, v172
	v_and_b32_e32 v0, 0xffff, v29
	v_mbcnt_lo_u32_b32 v7, s68, 0
	v_mbcnt_hi_u32_b32 v7, s69, v7
	v_add_lshl_u32 v0, v0, v7, 1
	v_cndmask_b32_e64 v0, v76, v0, s[68:69]
	ds_write_b16 v0, v6 offset:8704
	s_cbranch_vccz .Ltk_noeq_103
	s_cmp_eq_u32 s13, 0
	s_cbranch_scc1 .Ltk_noeq_103
	v_mbcnt_lo_u32_b32 v8, vcc_lo, 0
	v_mbcnt_hi_u32_b32 v8, vcc_hi, v8
	v_lshrrev_b32_e32 v1, 16, v29
	v_add3_u32 v1, v1, v8, s49
	v_cmp_gt_u32_e64 s[72:73], s84, v1
	v_lshlrev_b32_e32 v1, 1, v1
	s_and_b64 s[72:73], s[72:73], vcc
	s_nop 0
	v_cndmask_b32_e64 v1, v76, v1, s[72:73]
	ds_write_b16 v1, v6 offset:8704
.Ltk_noeq_103:
	v_cmp_lt_u32_e64 s[68:69], s14, v158
	v_cmp_eq_u32_e32 vcc, s14, v158
	v_and_b32_e32 v0, 0xffff, v30
	v_mbcnt_lo_u32_b32 v7, s68, 0
	v_mbcnt_hi_u32_b32 v7, s69, v7
	v_add_lshl_u32 v0, v0, v7, 1
	v_cndmask_b32_e64 v0, v76, v0, s[68:69]
	ds_write_b16 v0, v6 offset:9216
	s_cbranch_vccz .Ltk_noeq_104
	s_cmp_eq_u32 s14, 0
	s_cbranch_scc1 .Ltk_noeq_104
	v_mbcnt_lo_u32_b32 v8, vcc_lo, 0
	v_mbcnt_hi_u32_b32 v8, vcc_hi, v8
	v_lshrrev_b32_e32 v1, 16, v30
	v_add3_u32 v1, v1, v8, s50
	v_cmp_gt_u32_e64 s[72:73], s84, v1
	v_lshlrev_b32_e32 v1, 1, v1
	s_and_b64 s[72:73], s[72:73], vcc
	s_nop 0
	v_cndmask_b32_e64 v1, v76, v1, s[72:73]
	ds_write_b16 v1, v6 offset:9216
.Ltk_noeq_104:
	v_cmp_lt_u32_e64 s[68:69], s15, v133
	v_cmp_eq_u32_e32 vcc, s15, v133
	v_and_b32_e32 v0, 0xffff, v31
	v_mbcnt_lo_u32_b32 v7, s68, 0
	v_mbcnt_hi_u32_b32 v7, s69, v7
	v_add_lshl_u32 v0, v0, v7, 1
	v_cndmask_b32_e64 v0, v76, v0, s[68:69]
	ds_write_b16 v0, v6 offset:9728
	s_cbranch_vccz .Ltk_noeq_105
	s_cmp_eq_u32 s15, 0
	s_cbranch_scc1 .Ltk_noeq_105
	v_mbcnt_lo_u32_b32 v8, vcc_lo, 0
	v_mbcnt_hi_u32_b32 v8, vcc_hi, v8
	v_lshrrev_b32_e32 v1, 16, v31
	v_add3_u32 v1, v1, v8, s51
	v_cmp_gt_u32_e64 s[72:73], s84, v1
	v_lshlrev_b32_e32 v1, 1, v1
	s_and_b64 s[72:73], s[72:73], vcc
	s_nop 0
	v_cndmask_b32_e64 v1, v76, v1, s[72:73]
	ds_write_b16 v1, v6 offset:9728
.Ltk_noeq_105:
	s_add_i32 s28, s28, 8
	s_cmp_gt_u32 s28, s3
	s_cbranch_scc1 .Ltk_scat_done_93
	v_lshl_add_u32 v6, s28, 6, v101
	v_cmp_lt_u32_e64 s[68:69], s12, v186
	v_cmp_eq_u32_e32 vcc, s12, v186
	v_and_b32_e32 v0, 0xffff, v32
	v_mbcnt_lo_u32_b32 v7, s68, 0
	v_mbcnt_hi_u32_b32 v7, s69, v7
	v_add_lshl_u32 v0, v0, v7, 1
	v_cndmask_b32_e64 v0, v76, v0, s[68:69]
	ds_write_b16 v0, v6 offset:8192
	s_cbranch_vccz .Ltk_noeq_106
	s_cmp_eq_u32 s12, 0
	s_cbranch_scc1 .Ltk_noeq_106
	v_mbcnt_lo_u32_b32 v8, vcc_lo, 0
	v_mbcnt_hi_u32_b32 v8, vcc_hi, v8
	v_lshrrev_b32_e32 v1, 16, v32
	v_add3_u32 v1, v1, v8, s48
	v_cmp_gt_u32_e64 s[72:73], s84, v1
	v_lshlrev_b32_e32 v1, 1, v1
	s_and_b64 s[72:73], s[72:73], vcc
	s_nop 0
	v_cndmask_b32_e64 v1, v76, v1, s[72:73]
	ds_write_b16 v1, v6 offset:8192
.Ltk_noeq_106:
	v_cmp_lt_u32_e64 s[68:69], s13, v171
	v_cmp_eq_u32_e32 vcc, s13, v171
	v_and_b32_e32 v0, 0xffff, v33
	v_mbcnt_lo_u32_b32 v7, s68, 0
	v_mbcnt_hi_u32_b32 v7, s69, v7
	v_add_lshl_u32 v0, v0, v7, 1
	v_cndmask_b32_e64 v0, v76, v0, s[68:69]
	ds_write_b16 v0, v6 offset:8704
	s_cbranch_vccz .Ltk_noeq_107
	s_cmp_eq_u32 s13, 0
	s_cbranch_scc1 .Ltk_noeq_107
	v_mbcnt_lo_u32_b32 v8, vcc_lo, 0
	v_mbcnt_hi_u32_b32 v8, vcc_hi, v8
	v_lshrrev_b32_e32 v1, 16, v33
	v_add3_u32 v1, v1, v8, s49
	v_cmp_gt_u32_e64 s[72:73], s84, v1
	v_lshlrev_b32_e32 v1, 1, v1
	s_and_b64 s[72:73], s[72:73], vcc
	s_nop 0
	v_cndmask_b32_e64 v1, v76, v1, s[72:73]
	ds_write_b16 v1, v6 offset:8704
.Ltk_noeq_107:
	v_cmp_lt_u32_e64 s[68:69], s14, v153
	v_cmp_eq_u32_e32 vcc, s14, v153
	v_and_b32_e32 v0, 0xffff, v34
	v_mbcnt_lo_u32_b32 v7, s68, 0
	v_mbcnt_hi_u32_b32 v7, s69, v7
	v_add_lshl_u32 v0, v0, v7, 1
	v_cndmask_b32_e64 v0, v76, v0, s[68:69]
	ds_write_b16 v0, v6 offset:9216
	s_cbranch_vccz .Ltk_noeq_108
	s_cmp_eq_u32 s14, 0
	s_cbranch_scc1 .Ltk_noeq_108
	v_mbcnt_lo_u32_b32 v8, vcc_lo, 0
	v_mbcnt_hi_u32_b32 v8, vcc_hi, v8
	v_lshrrev_b32_e32 v1, 16, v34
	v_add3_u32 v1, v1, v8, s50
	v_cmp_gt_u32_e64 s[72:73], s84, v1
	v_lshlrev_b32_e32 v1, 1, v1
	s_and_b64 s[72:73], s[72:73], vcc
	s_nop 0
	v_cndmask_b32_e64 v1, v76, v1, s[72:73]
	ds_write_b16 v1, v6 offset:9216
.Ltk_noeq_108:
	v_cmp_lt_u32_e64 s[68:69], s15, v129
	v_cmp_eq_u32_e32 vcc, s15, v129
	v_and_b32_e32 v0, 0xffff, v35
	v_mbcnt_lo_u32_b32 v7, s68, 0
	v_mbcnt_hi_u32_b32 v7, s69, v7
	v_add_lshl_u32 v0, v0, v7, 1
	v_cndmask_b32_e64 v0, v76, v0, s[68:69]
	ds_write_b16 v0, v6 offset:9728
	s_cbranch_vccz .Ltk_noeq_109
	s_cmp_eq_u32 s15, 0
	s_cbranch_scc1 .Ltk_noeq_109
	v_mbcnt_lo_u32_b32 v8, vcc_lo, 0
	v_mbcnt_hi_u32_b32 v8, vcc_hi, v8
	v_lshrrev_b32_e32 v1, 16, v35
	v_add3_u32 v1, v1, v8, s51
	v_cmp_gt_u32_e64 s[72:73], s84, v1
	v_lshlrev_b32_e32 v1, 1, v1
	s_and_b64 s[72:73], s[72:73], vcc
	s_nop 0
	v_cndmask_b32_e64 v1, v76, v1, s[72:73]
	ds_write_b16 v1, v6 offset:9728
.Ltk_noeq_109:
	s_add_i32 s28, s28, 8
	s_cmp_gt_u32 s28, s3
	s_cbranch_scc1 .Ltk_scat_done_93
	v_lshl_add_u32 v6, s28, 6, v101
	v_cmp_lt_u32_e64 s[68:69], s12, v185
	v_cmp_eq_u32_e32 vcc, s12, v185
	v_and_b32_e32 v0, 0xffff, v36
	v_mbcnt_lo_u32_b32 v7, s68, 0
	v_mbcnt_hi_u32_b32 v7, s69, v7
	v_add_lshl_u32 v0, v0, v7, 1
	v_cndmask_b32_e64 v0, v76, v0, s[68:69]
	ds_write_b16 v0, v6 offset:8192
	s_cbranch_vccz .Ltk_noeq_110
	s_cmp_eq_u32 s12, 0
	s_cbranch_scc1 .Ltk_noeq_110
	v_mbcnt_lo_u32_b32 v8, vcc_lo, 0
	v_mbcnt_hi_u32_b32 v8, vcc_hi, v8
	v_lshrrev_b32_e32 v1, 16, v36
	v_add3_u32 v1, v1, v8, s48
	v_cmp_gt_u32_e64 s[72:73], s84, v1
	v_lshlrev_b32_e32 v1, 1, v1
	s_and_b64 s[72:73], s[72:73], vcc
	s_nop 0
	v_cndmask_b32_e64 v1, v76, v1, s[72:73]
	ds_write_b16 v1, v6 offset:8192
; DI void topk_job(const Params& p, int b, int t0, char* lds) {
;     ...
;   const unsigned long long lt = (1ull << lane) - 1ull;
; #pragma unroll
;   for (int i = 0; i < 17; ++i) {
;     const int c = 1 + w + 8 * i;
;     if (c <= cmax) {
;       const int key = c * 64 + lane;
; #pragma unroll
;       for (int q = 0; q < 4; ++q) {
;         u16* out = p.IDX + (size_t)(b * PP + t0 + q) * 256;
;         const bool gt = sc[i][q] > T[q];
;         const bool eq = (sc[i][q] == T[q]) && (T[q] != 0u);
;         const unsigned long long m1 = __ballot(gt), m2 = __ballot(eq);
;         if ((m1 | m2) != 0ull) {
;           const unsigned bb = baseb[q * 132 + c];
;           if (gt) out[(int)(bb & 0xffffu) + __popcll(m1 & lt)] = (u16)key;
;           if (eq) { const int pos = ng[q] + (int)(bb >> 16) + __popcll(m2 & lt); if (pos < 256) out[pos] = (u16)key; }
;         }
;       }
;     }
;   }
.Ltk_noeq_110:
	v_cmp_lt_u32_e64 s[68:69], s13, v170
	v_cmp_eq_u32_e32 vcc, s13, v170
	v_and_b32_e32 v0, 0xffff, v37
	v_mbcnt_lo_u32_b32 v7, s68, 0
	v_mbcnt_hi_u32_b32 v7, s69, v7
	v_add_lshl_u32 v0, v0, v7, 1
	v_cndmask_b32_e64 v0, v76, v0, s[68:69]
	ds_write_b16 v0, v6 offset:8704
	s_cbranch_vccz .Ltk_noeq_111
	s_cmp_eq_u32 s13, 0
	s_cbranch_scc1 .Ltk_noeq_111
	v_mbcnt_lo_u32_b32 v8, vcc_lo, 0
	v_mbcnt_hi_u32_b32 v8, vcc_hi, v8
	v_lshrrev_b32_e32 v1, 16, v37
	v_add3_u32 v1, v1, v8, s49
	v_cmp_gt_u32_e64 s[72:73], s84, v1
	v_lshlrev_b32_e32 v1, 1, v1
	s_and_b64 s[72:73], s[72:73], vcc
	s_nop 0
	v_cndmask_b32_e64 v1, v76, v1, s[72:73]
	ds_write_b16 v1, v6 offset:8704
.Ltk_noeq_111:
	v_cmp_lt_u32_e64 s[68:69], s14, v150
	v_cmp_eq_u32_e32 vcc, s14, v150
	v_and_b32_e32 v0, 0xffff, v38
	v_mbcnt_lo_u32_b32 v7, s68, 0
	v_mbcnt_hi_u32_b32 v7, s69, v7
	v_add_lshl_u32 v0, v0, v7, 1
	v_cndmask_b32_e64 v0, v76, v0, s[68:69]
	ds_write_b16 v0, v6 offset:9216
	s_cbranch_vccz .Ltk_noeq_112
	s_cmp_eq_u32 s14, 0
	s_cbranch_scc1 .Ltk_noeq_112
	v_mbcnt_lo_u32_b32 v8, vcc_lo, 0
	v_mbcnt_hi_u32_b32 v8, vcc_hi, v8
	v_lshrrev_b32_e32 v1, 16, v38
	v_add3_u32 v1, v1, v8, s50
	v_cmp_gt_u32_e64 s[72:73], s84, v1
	v_lshlrev_b32_e32 v1, 1, v1
	s_and_b64 s[72:73], s[72:73], vcc
	s_nop 0
	v_cndmask_b32_e64 v1, v76, v1, s[72:73]
	ds_write_b16 v1, v6 offset:9216
.Ltk_noeq_112:
	v_cmp_lt_u32_e64 s[68:69], s15, v127
	v_cmp_eq_u32_e32 vcc, s15, v127
	v_and_b32_e32 v0, 0xffff, v39
	v_mbcnt_lo_u32_b32 v7, s68, 0
	v_mbcnt_hi_u32_b32 v7, s69, v7
	v_add_lshl_u32 v0, v0, v7, 1
	v_cndmask_b32_e64 v0, v76, v0, s[68:69]
	ds_write_b16 v0, v6 offset:9728
	s_cbranch_vccz .Ltk_noeq_113
	s_cmp_eq_u32 s15, 0
	s_cbranch_scc1 .Ltk_noeq_113
	v_mbcnt_lo_u32_b32 v8, vcc_lo, 0
	v_mbcnt_hi_u32_b32 v8, vcc_hi, v8
	v_lshrrev_b32_e32 v1, 16, v39
	v_add3_u32 v1, v1, v8, s51
	v_cmp_gt_u32_e64 s[72:73], s84, v1
	v_lshlrev_b32_e32 v1, 1, v1
	s_and_b64 s[72:73], s[72:73], vcc
	s_nop 0
	v_cndmask_b32_e64 v1, v76, v1, s[72:73]
	ds_write_b16 v1, v6 offset:9728
.Ltk_noeq_113:
	s_add_i32 s28, s28, 8
	s_cmp_gt_u32 s28, s3
	s_cbranch_scc1 .Ltk_scat_done_93
	v_lshl_add_u32 v6, s28, 6, v101
	v_cmp_lt_u32_e64 s[68:69], s12, v184
	v_cmp_eq_u32_e32 vcc, s12, v184
	v_and_b32_e32 v0, 0xffff, v40
	v_mbcnt_lo_u32_b32 v7, s68, 0
	v_mbcnt_hi_u32_b32 v7, s69, v7
	v_add_lshl_u32 v0, v0, v7, 1
	v_cndmask_b32_e64 v0, v76, v0, s[68:69]
	ds_write_b16 v0, v6 offset:8192
	s_cbranch_vccz .Ltk_noeq_114
	s_cmp_eq_u32 s12, 0
	s_cbranch_scc1 .Ltk_noeq_114
	v_mbcnt_lo_u32_b32 v8, vcc_lo, 0
	v_mbcnt_hi_u32_b32 v8, vcc_hi, v8
	v_lshrrev_b32_e32 v1, 16, v40
	v_add3_u32 v1, v1, v8, s48
	v_cmp_gt_u32_e64 s[72:73], s84, v1
	v_lshlrev_b32_e32 v1, 1, v1
	s_and_b64 s[72:73], s[72:73], vcc
	s_nop 0
	v_cndmask_b32_e64 v1, v76, v1, s[72:73]
	ds_write_b16 v1, v6 offset:8192
.Ltk_noeq_114:
	v_cmp_lt_u32_e64 s[68:69], s13, v168
	v_cmp_eq_u32_e32 vcc, s13, v168
	v_and_b32_e32 v0, 0xffff, v41
	v_mbcnt_lo_u32_b32 v7, s68, 0
	v_mbcnt_hi_u32_b32 v7, s69, v7
	v_add_lshl_u32 v0, v0, v7, 1
	v_cndmask_b32_e64 v0, v76, v0, s[68:69]
	ds_write_b16 v0, v6 offset:8704
	s_cbranch_vccz .Ltk_noeq_115
	s_cmp_eq_u32 s13, 0
	s_cbranch_scc1 .Ltk_noeq_115
	v_mbcnt_lo_u32_b32 v8, vcc_lo, 0
	v_mbcnt_hi_u32_b32 v8, vcc_hi, v8
	v_lshrrev_b32_e32 v1, 16, v41
	v_add3_u32 v1, v1, v8, s49
	v_cmp_gt_u32_e64 s[72:73], s84, v1
	v_lshlrev_b32_e32 v1, 1, v1
	s_and_b64 s[72:73], s[72:73], vcc
	s_nop 0
	v_cndmask_b32_e64 v1, v76, v1, s[72:73]
	ds_write_b16 v1, v6 offset:8704
.Ltk_noeq_115:
	v_cmp_lt_u32_e64 s[68:69], s14, v149
	v_cmp_eq_u32_e32 vcc, s14, v149
	v_and_b32_e32 v0, 0xffff, v42
	v_mbcnt_lo_u32_b32 v7, s68, 0
	v_mbcnt_hi_u32_b32 v7, s69, v7
	v_add_lshl_u32 v0, v0, v7, 1
	v_cndmask_b32_e64 v0, v76, v0, s[68:69]
	ds_write_b16 v0, v6 offset:9216
	s_cbranch_vccz .Ltk_noeq_116
	s_cmp_eq_u32 s14, 0
	s_cbranch_scc1 .Ltk_noeq_116
	v_mbcnt_lo_u32_b32 v8, vcc_lo, 0
	v_mbcnt_hi_u32_b32 v8, vcc_hi, v8
	v_lshrrev_b32_e32 v1, 16, v42
	v_add3_u32 v1, v1, v8, s50
	v_cmp_gt_u32_e64 s[72:73], s84, v1
	v_lshlrev_b32_e32 v1, 1, v1
	s_and_b64 s[72:73], s[72:73], vcc
	s_nop 0
	v_cndmask_b32_e64 v1, v76, v1, s[72:73]
	ds_write_b16 v1, v6 offset:9216
.Ltk_noeq_116:
	v_cmp_lt_u32_e64 s[68:69], s15, v125
	v_cmp_eq_u32_e32 vcc, s15, v125
	v_and_b32_e32 v0, 0xffff, v43
	v_mbcnt_lo_u32_b32 v7, s68, 0
	v_mbcnt_hi_u32_b32 v7, s69, v7
	v_add_lshl_u32 v0, v0, v7, 1
	v_cndmask_b32_e64 v0, v76, v0, s[68:69]
	ds_write_b16 v0, v6 offset:9728
	s_cbranch_vccz .Ltk_noeq_117
	s_cmp_eq_u32 s15, 0
	s_cbranch_scc1 .Ltk_noeq_117
	v_mbcnt_lo_u32_b32 v8, vcc_lo, 0
	v_mbcnt_hi_u32_b32 v8, vcc_hi, v8
	v_lshrrev_b32_e32 v1, 16, v43
	v_add3_u32 v1, v1, v8, s51
	v_cmp_gt_u32_e64 s[72:73], s84, v1
	v_lshlrev_b32_e32 v1, 1, v1
	s_and_b64 s[72:73], s[72:73], vcc
	s_nop 0
	v_cndmask_b32_e64 v1, v76, v1, s[72:73]
	ds_write_b16 v1, v6 offset:9728
.Ltk_noeq_117:
	s_add_i32 s28, s28, 8
	s_cmp_gt_u32 s28, s3
	s_cbranch_scc1 .Ltk_scat_done_93
	v_lshl_add_u32 v6, s28, 6, v101
	v_cmp_lt_u32_e64 s[68:69], s12, v183
	v_cmp_eq_u32_e32 vcc, s12, v183
	v_and_b32_e32 v0, 0xffff, v44
	v_mbcnt_lo_u32_b32 v7, s68, 0
	v_mbcnt_hi_u32_b32 v7, s69, v7
	v_add_lshl_u32 v0, v0, v7, 1
	v_cndmask_b32_e64 v0, v76, v0, s[68:69]
	ds_write_b16 v0, v6 offset:8192
	s_cbranch_vccz .Ltk_noeq_118
	s_cmp_eq_u32 s12, 0
	s_cbranch_scc1 .Ltk_noeq_118
	v_mbcnt_lo_u32_b32 v8, vcc_lo, 0
	v_mbcnt_hi_u32_b32 v8, vcc_hi, v8
	v_lshrrev_b32_e32 v1, 16, v44
	v_add3_u32 v1, v1, v8, s48
	v_cmp_gt_u32_e64 s[72:73], s84, v1
	v_lshlrev_b32_e32 v1, 1, v1
	s_and_b64 s[72:73], s[72:73], vcc
	s_nop 0
	v_cndmask_b32_e64 v1, v76, v1, s[72:73]
	ds_write_b16 v1, v6 offset:8192
; DI void topk_job(const Params& p, int b, int t0, char* lds) {
;     ...
;   const unsigned long long lt = (1ull << lane) - 1ull;
; #pragma unroll
;   for (int i = 0; i < 17; ++i) {
;     const int c = 1 + w + 8 * i;
;     if (c <= cmax) {
;       const int key = c * 64 + lane;
; #pragma unroll
;       for (int q = 0; q < 4; ++q) {
;         u16* out = p.IDX + (size_t)(b * PP + t0 + q) * 256;
;         const bool gt = sc[i][q] > T[q];
;         const bool eq = (sc[i][q] == T[q]) && (T[q] != 0u);
;         const unsigned long long m1 = __ballot(gt), m2 = __ballot(eq);
;         if ((m1 | m2) != 0ull) {
;           const unsigned bb = baseb[q * 132 + c];
;           if (gt) out[(int)(bb & 0xffffu) + __popcll(m1 & lt)] = (u16)key;
;           if (eq) { const int pos = ng[q] + (int)(bb >> 16) + __popcll(m2 & lt); if (pos < 256) out[pos] = (u16)key; }
;         }
;       }
;     }
;   }
.Ltk_noeq_118:
	v_cmp_lt_u32_e64 s[68:69], s13, v167
	v_cmp_eq_u32_e32 vcc, s13, v167
	v_and_b32_e32 v0, 0xffff, v45
	v_mbcnt_lo_u32_b32 v7, s68, 0
	v_mbcnt_hi_u32_b32 v7, s69, v7
	v_add_lshl_u32 v0, v0, v7, 1
	v_cndmask_b32_e64 v0, v76, v0, s[68:69]
	ds_write_b16 v0, v6 offset:8704
	s_cbranch_vccz .Ltk_noeq_119
	s_cmp_eq_u32 s13, 0
	s_cbranch_scc1 .Ltk_noeq_119
	v_mbcnt_lo_u32_b32 v8, vcc_lo, 0
	v_mbcnt_hi_u32_b32 v8, vcc_hi, v8
	v_lshrrev_b32_e32 v1, 16, v45
	v_add3_u32 v1, v1, v8, s49
	v_cmp_gt_u32_e64 s[72:73], s84, v1
	v_lshlrev_b32_e32 v1, 1, v1
	s_and_b64 s[72:73], s[72:73], vcc
	s_nop 0
	v_cndmask_b32_e64 v1, v76, v1, s[72:73]
	ds_write_b16 v1, v6 offset:8704
.Ltk_noeq_119:
	v_cmp_lt_u32_e64 s[68:69], s14, v147
	v_cmp_eq_u32_e32 vcc, s14, v147
	v_and_b32_e32 v0, 0xffff, v46
	v_mbcnt_lo_u32_b32 v7, s68, 0
	v_mbcnt_hi_u32_b32 v7, s69, v7
	v_add_lshl_u32 v0, v0, v7, 1
	v_cndmask_b32_e64 v0, v76, v0, s[68:69]
	ds_write_b16 v0, v6 offset:9216
	s_cbranch_vccz .Ltk_noeq_120
	s_cmp_eq_u32 s14, 0
	s_cbranch_scc1 .Ltk_noeq_120
	v_mbcnt_lo_u32_b32 v8, vcc_lo, 0
	v_mbcnt_hi_u32_b32 v8, vcc_hi, v8
	v_lshrrev_b32_e32 v1, 16, v46
	v_add3_u32 v1, v1, v8, s50
	v_cmp_gt_u32_e64 s[72:73], s84, v1
	v_lshlrev_b32_e32 v1, 1, v1
	s_and_b64 s[72:73], s[72:73], vcc
	s_nop 0
	v_cndmask_b32_e64 v1, v76, v1, s[72:73]
	ds_write_b16 v1, v6 offset:9216
.Ltk_noeq_120:
	v_cmp_lt_u32_e64 s[68:69], s15, v123
	v_cmp_eq_u32_e32 vcc, s15, v123
	v_and_b32_e32 v0, 0xffff, v47
	v_mbcnt_lo_u32_b32 v7, s68, 0
	v_mbcnt_hi_u32_b32 v7, s69, v7
	v_add_lshl_u32 v0, v0, v7, 1
	v_cndmask_b32_e64 v0, v76, v0, s[68:69]
	ds_write_b16 v0, v6 offset:9728
	s_cbranch_vccz .Ltk_noeq_121
	s_cmp_eq_u32 s15, 0
	s_cbranch_scc1 .Ltk_noeq_121
	v_mbcnt_lo_u32_b32 v8, vcc_lo, 0
	v_mbcnt_hi_u32_b32 v8, vcc_hi, v8
	v_lshrrev_b32_e32 v1, 16, v47
	v_add3_u32 v1, v1, v8, s51
	v_cmp_gt_u32_e64 s[72:73], s84, v1
	v_lshlrev_b32_e32 v1, 1, v1
	s_and_b64 s[72:73], s[72:73], vcc
	s_nop 0
	v_cndmask_b32_e64 v1, v76, v1, s[72:73]
	ds_write_b16 v1, v6 offset:9728
.Ltk_noeq_121:
	s_add_i32 s28, s28, 8
	s_cmp_gt_u32 s28, s3
	s_cbranch_scc1 .Ltk_scat_done_93
	v_lshl_add_u32 v6, s28, 6, v101
	v_cmp_lt_u32_e64 s[68:69], s12, v182
	v_cmp_eq_u32_e32 vcc, s12, v182
	v_and_b32_e32 v0, 0xffff, v48
	v_mbcnt_lo_u32_b32 v7, s68, 0
	v_mbcnt_hi_u32_b32 v7, s69, v7
	v_add_lshl_u32 v0, v0, v7, 1
	v_cndmask_b32_e64 v0, v76, v0, s[68:69]
	ds_write_b16 v0, v6 offset:8192
	s_cbranch_vccz .Ltk_noeq_122
	s_cmp_eq_u32 s12, 0
	s_cbranch_scc1 .Ltk_noeq_122
	v_mbcnt_lo_u32_b32 v8, vcc_lo, 0
	v_mbcnt_hi_u32_b32 v8, vcc_hi, v8
	v_lshrrev_b32_e32 v1, 16, v48
	v_add3_u32 v1, v1, v8, s48
	v_cmp_gt_u32_e64 s[72:73], s84, v1
	v_lshlrev_b32_e32 v1, 1, v1
	s_and_b64 s[72:73], s[72:73], vcc
	s_nop 0
	v_cndmask_b32_e64 v1, v76, v1, s[72:73]
	ds_write_b16 v1, v6 offset:8192
.Ltk_noeq_122:
	v_cmp_lt_u32_e64 s[68:69], s13, v166
	v_cmp_eq_u32_e32 vcc, s13, v166
	v_and_b32_e32 v0, 0xffff, v49
	v_mbcnt_lo_u32_b32 v7, s68, 0
	v_mbcnt_hi_u32_b32 v7, s69, v7
	v_add_lshl_u32 v0, v0, v7, 1
	v_cndmask_b32_e64 v0, v76, v0, s[68:69]
	ds_write_b16 v0, v6 offset:8704
	s_cbranch_vccz .Ltk_noeq_123
	s_cmp_eq_u32 s13, 0
	s_cbranch_scc1 .Ltk_noeq_123
	v_mbcnt_lo_u32_b32 v8, vcc_lo, 0
	v_mbcnt_hi_u32_b32 v8, vcc_hi, v8
	v_lshrrev_b32_e32 v1, 16, v49
	v_add3_u32 v1, v1, v8, s49
	v_cmp_gt_u32_e64 s[72:73], s84, v1
	v_lshlrev_b32_e32 v1, 1, v1
	s_and_b64 s[72:73], s[72:73], vcc
	s_nop 0
	v_cndmask_b32_e64 v1, v76, v1, s[72:73]
	ds_write_b16 v1, v6 offset:8704
.Ltk_noeq_123:
	v_cmp_lt_u32_e64 s[68:69], s14, v146
	v_cmp_eq_u32_e32 vcc, s14, v146
	v_and_b32_e32 v0, 0xffff, v50
	v_mbcnt_lo_u32_b32 v7, s68, 0
	v_mbcnt_hi_u32_b32 v7, s69, v7
	v_add_lshl_u32 v0, v0, v7, 1
	v_cndmask_b32_e64 v0, v76, v0, s[68:69]
	ds_write_b16 v0, v6 offset:9216
	s_cbranch_vccz .Ltk_noeq_124
	s_cmp_eq_u32 s14, 0
	s_cbranch_scc1 .Ltk_noeq_124
	v_mbcnt_lo_u32_b32 v8, vcc_lo, 0
	v_mbcnt_hi_u32_b32 v8, vcc_hi, v8
	v_lshrrev_b32_e32 v1, 16, v50
	v_add3_u32 v1, v1, v8, s50
	v_cmp_gt_u32_e64 s[72:73], s84, v1
	v_lshlrev_b32_e32 v1, 1, v1
	s_and_b64 s[72:73], s[72:73], vcc
	s_nop 0
	v_cndmask_b32_e64 v1, v76, v1, s[72:73]
	ds_write_b16 v1, v6 offset:9216
.Ltk_noeq_124:
	v_cmp_lt_u32_e64 s[68:69], s15, v121
	v_cmp_eq_u32_e32 vcc, s15, v121
	v_and_b32_e32 v0, 0xffff, v51
	v_mbcnt_lo_u32_b32 v7, s68, 0
	v_mbcnt_hi_u32_b32 v7, s69, v7
	v_add_lshl_u32 v0, v0, v7, 1
	v_cndmask_b32_e64 v0, v76, v0, s[68:69]
	ds_write_b16 v0, v6 offset:9728
	s_cbranch_vccz .Ltk_noeq_125
	s_cmp_eq_u32 s15, 0
	s_cbranch_scc1 .Ltk_noeq_125
	v_mbcnt_lo_u32_b32 v8, vcc_lo, 0
	v_mbcnt_hi_u32_b32 v8, vcc_hi, v8
	v_lshrrev_b32_e32 v1, 16, v51
	v_add3_u32 v1, v1, v8, s51
	v_cmp_gt_u32_e64 s[72:73], s84, v1
	v_lshlrev_b32_e32 v1, 1, v1
	s_and_b64 s[72:73], s[72:73], vcc
	s_nop 0
	v_cndmask_b32_e64 v1, v76, v1, s[72:73]
	ds_write_b16 v1, v6 offset:9728
.Ltk_noeq_125:
	s_add_i32 s28, s28, 8
	s_cmp_gt_u32 s28, s3
	s_cbranch_scc1 .Ltk_scat_done_93
	v_lshl_add_u32 v6, s28, 6, v101
	v_cmp_lt_u32_e64 s[68:69], s12, v181
	v_cmp_eq_u32_e32 vcc, s12, v181
	v_and_b32_e32 v0, 0xffff, v52
	v_mbcnt_lo_u32_b32 v7, s68, 0
	v_mbcnt_hi_u32_b32 v7, s69, v7
	v_add_lshl_u32 v0, v0, v7, 1
	v_cndmask_b32_e64 v0, v76, v0, s[68:69]
	ds_write_b16 v0, v6 offset:8192
	s_cbranch_vccz .Ltk_noeq_126
	s_cmp_eq_u32 s12, 0
	s_cbranch_scc1 .Ltk_noeq_126
	v_mbcnt_lo_u32_b32 v8, vcc_lo, 0
	v_mbcnt_hi_u32_b32 v8, vcc_hi, v8
	v_lshrrev_b32_e32 v1, 16, v52
	v_add3_u32 v1, v1, v8, s48
	v_cmp_gt_u32_e64 s[72:73], s84, v1
	v_lshlrev_b32_e32 v1, 1, v1
	s_and_b64 s[72:73], s[72:73], vcc
	s_nop 0
	v_cndmask_b32_e64 v1, v76, v1, s[72:73]
	ds_write_b16 v1, v6 offset:8192
; DI void topk_job(const Params& p, int b, int t0, char* lds) {
;     ...
;   const unsigned long long lt = (1ull << lane) - 1ull;
; #pragma unroll
;   for (int i = 0; i < 17; ++i) {
;     const int c = 1 + w + 8 * i;
;     if (c <= cmax) {
;       const int key = c * 64 + lane;
; #pragma unroll
;       for (int q = 0; q < 4; ++q) {
;         u16* out = p.IDX + (size_t)(b * PP + t0 + q) * 256;
;         const bool gt = sc[i][q] > T[q];
;         const bool eq = (sc[i][q] == T[q]) && (T[q] != 0u);
;         const unsigned long long m1 = __ballot(gt), m2 = __ballot(eq);
;         if ((m1 | m2) != 0ull) {
;           const unsigned bb = baseb[q * 132 + c];
;           if (gt) out[(int)(bb & 0xffffu) + __popcll(m1 & lt)] = (u16)key;
;           if (eq) { const int pos = ng[q] + (int)(bb >> 16) + __popcll(m2 & lt); if (pos < 256) out[pos] = (u16)key; }
;         }
;       }
;     }
;   }
.Ltk_noeq_126:
	v_cmp_lt_u32_e64 s[68:69], s13, v165
	v_cmp_eq_u32_e32 vcc, s13, v165
	v_and_b32_e32 v0, 0xffff, v53
	v_mbcnt_lo_u32_b32 v7, s68, 0
	v_mbcnt_hi_u32_b32 v7, s69, v7
	v_add_lshl_u32 v0, v0, v7, 1
	v_cndmask_b32_e64 v0, v76, v0, s[68:69]
	ds_write_b16 v0, v6 offset:8704
	s_cbranch_vccz .Ltk_noeq_127
	s_cmp_eq_u32 s13, 0
	s_cbranch_scc1 .Ltk_noeq_127
	v_mbcnt_lo_u32_b32 v8, vcc_lo, 0
	v_mbcnt_hi_u32_b32 v8, vcc_hi, v8
	v_lshrrev_b32_e32 v1, 16, v53
	v_add3_u32 v1, v1, v8, s49
	v_cmp_gt_u32_e64 s[72:73], s84, v1
	v_lshlrev_b32_e32 v1, 1, v1
	s_and_b64 s[72:73], s[72:73], vcc
	s_nop 0
	v_cndmask_b32_e64 v1, v76, v1, s[72:73]
	ds_write_b16 v1, v6 offset:8704
.Ltk_noeq_127:
	v_cmp_lt_u32_e64 s[68:69], s14, v145
	v_cmp_eq_u32_e32 vcc, s14, v145
	v_and_b32_e32 v0, 0xffff, v54
	v_mbcnt_lo_u32_b32 v7, s68, 0
	v_mbcnt_hi_u32_b32 v7, s69, v7
	v_add_lshl_u32 v0, v0, v7, 1
	v_cndmask_b32_e64 v0, v76, v0, s[68:69]
	ds_write_b16 v0, v6 offset:9216
	s_cbranch_vccz .Ltk_noeq_128
	s_cmp_eq_u32 s14, 0
	s_cbranch_scc1 .Ltk_noeq_128
	v_mbcnt_lo_u32_b32 v8, vcc_lo, 0
	v_mbcnt_hi_u32_b32 v8, vcc_hi, v8
	v_lshrrev_b32_e32 v1, 16, v54
	v_add3_u32 v1, v1, v8, s50
	v_cmp_gt_u32_e64 s[72:73], s84, v1
	v_lshlrev_b32_e32 v1, 1, v1
	s_and_b64 s[72:73], s[72:73], vcc
	s_nop 0
	v_cndmask_b32_e64 v1, v76, v1, s[72:73]
	ds_write_b16 v1, v6 offset:9216
.Ltk_noeq_128:
	v_cmp_lt_u32_e64 s[68:69], s15, v119
	v_cmp_eq_u32_e32 vcc, s15, v119
	v_and_b32_e32 v0, 0xffff, v55
	v_mbcnt_lo_u32_b32 v7, s68, 0
	v_mbcnt_hi_u32_b32 v7, s69, v7
	v_add_lshl_u32 v0, v0, v7, 1
	v_cndmask_b32_e64 v0, v76, v0, s[68:69]
	ds_write_b16 v0, v6 offset:9728
	s_cbranch_vccz .Ltk_noeq_129
	s_cmp_eq_u32 s15, 0
	s_cbranch_scc1 .Ltk_noeq_129
	v_mbcnt_lo_u32_b32 v8, vcc_lo, 0
	v_mbcnt_hi_u32_b32 v8, vcc_hi, v8
	v_lshrrev_b32_e32 v1, 16, v55
	v_add3_u32 v1, v1, v8, s51
	v_cmp_gt_u32_e64 s[72:73], s84, v1
	v_lshlrev_b32_e32 v1, 1, v1
	s_and_b64 s[72:73], s[72:73], vcc
	s_nop 0
	v_cndmask_b32_e64 v1, v76, v1, s[72:73]
	ds_write_b16 v1, v6 offset:9728
.Ltk_noeq_129:
	s_add_i32 s28, s28, 8
	s_cmp_gt_u32 s28, s3
	s_cbranch_scc1 .Ltk_scat_done_93
	v_lshl_add_u32 v6, s28, 6, v101
	v_cmp_lt_u32_e64 s[68:69], s12, v180
	v_cmp_eq_u32_e32 vcc, s12, v180
	v_and_b32_e32 v0, 0xffff, v56
	v_mbcnt_lo_u32_b32 v7, s68, 0
	v_mbcnt_hi_u32_b32 v7, s69, v7
	v_add_lshl_u32 v0, v0, v7, 1
	v_cndmask_b32_e64 v0, v76, v0, s[68:69]
	ds_write_b16 v0, v6 offset:8192
	s_cbranch_vccz .Ltk_noeq_130
	s_cmp_eq_u32 s12, 0
	s_cbranch_scc1 .Ltk_noeq_130
	v_mbcnt_lo_u32_b32 v8, vcc_lo, 0
	v_mbcnt_hi_u32_b32 v8, vcc_hi, v8
	v_lshrrev_b32_e32 v1, 16, v56
	v_add3_u32 v1, v1, v8, s48
	v_cmp_gt_u32_e64 s[72:73], s84, v1
	v_lshlrev_b32_e32 v1, 1, v1
	s_and_b64 s[72:73], s[72:73], vcc
	s_nop 0
	v_cndmask_b32_e64 v1, v76, v1, s[72:73]
	ds_write_b16 v1, v6 offset:8192
.Ltk_noeq_130:
	v_cmp_lt_u32_e64 s[68:69], s13, v164
	v_cmp_eq_u32_e32 vcc, s13, v164
	v_and_b32_e32 v0, 0xffff, v57
	v_mbcnt_lo_u32_b32 v7, s68, 0
	v_mbcnt_hi_u32_b32 v7, s69, v7
	v_add_lshl_u32 v0, v0, v7, 1
	v_cndmask_b32_e64 v0, v76, v0, s[68:69]
	ds_write_b16 v0, v6 offset:8704
	s_cbranch_vccz .Ltk_noeq_131
	s_cmp_eq_u32 s13, 0
	s_cbranch_scc1 .Ltk_noeq_131
	v_mbcnt_lo_u32_b32 v8, vcc_lo, 0
	v_mbcnt_hi_u32_b32 v8, vcc_hi, v8
	v_lshrrev_b32_e32 v1, 16, v57
	v_add3_u32 v1, v1, v8, s49
	v_cmp_gt_u32_e64 s[72:73], s84, v1
	v_lshlrev_b32_e32 v1, 1, v1
	s_and_b64 s[72:73], s[72:73], vcc
	s_nop 0
	v_cndmask_b32_e64 v1, v76, v1, s[72:73]
	ds_write_b16 v1, v6 offset:8704
.Ltk_noeq_131:
	v_cmp_lt_u32_e64 s[68:69], s14, v143
	v_cmp_eq_u32_e32 vcc, s14, v143
	v_and_b32_e32 v0, 0xffff, v58
	v_mbcnt_lo_u32_b32 v7, s68, 0
	v_mbcnt_hi_u32_b32 v7, s69, v7
	v_add_lshl_u32 v0, v0, v7, 1
	v_cndmask_b32_e64 v0, v76, v0, s[68:69]
	ds_write_b16 v0, v6 offset:9216
	s_cbranch_vccz .Ltk_noeq_132
	s_cmp_eq_u32 s14, 0
	s_cbranch_scc1 .Ltk_noeq_132
	v_mbcnt_lo_u32_b32 v8, vcc_lo, 0
	v_mbcnt_hi_u32_b32 v8, vcc_hi, v8
	v_lshrrev_b32_e32 v1, 16, v58
	v_add3_u32 v1, v1, v8, s50
	v_cmp_gt_u32_e64 s[72:73], s84, v1
	v_lshlrev_b32_e32 v1, 1, v1
	s_and_b64 s[72:73], s[72:73], vcc
	s_nop 0
	v_cndmask_b32_e64 v1, v76, v1, s[72:73]
	ds_write_b16 v1, v6 offset:9216
.Ltk_noeq_132:
	v_cmp_lt_u32_e64 s[68:69], s15, v115
	v_cmp_eq_u32_e32 vcc, s15, v115
	v_and_b32_e32 v0, 0xffff, v59
	v_mbcnt_lo_u32_b32 v7, s68, 0
	v_mbcnt_hi_u32_b32 v7, s69, v7
	v_add_lshl_u32 v0, v0, v7, 1
	v_cndmask_b32_e64 v0, v76, v0, s[68:69]
	ds_write_b16 v0, v6 offset:9728
	s_cbranch_vccz .Ltk_noeq_133
	s_cmp_eq_u32 s15, 0
	s_cbranch_scc1 .Ltk_noeq_133
	v_mbcnt_lo_u32_b32 v8, vcc_lo, 0
	v_mbcnt_hi_u32_b32 v8, vcc_hi, v8
	v_lshrrev_b32_e32 v1, 16, v59
	v_add3_u32 v1, v1, v8, s51
	v_cmp_gt_u32_e64 s[72:73], s84, v1
	v_lshlrev_b32_e32 v1, 1, v1
	s_and_b64 s[72:73], s[72:73], vcc
	s_nop 0
	v_cndmask_b32_e64 v1, v76, v1, s[72:73]
	ds_write_b16 v1, v6 offset:9728
.Ltk_noeq_133:
	s_add_i32 s28, s28, 8
	s_cmp_gt_u32 s28, s3
	s_cbranch_scc1 .Ltk_scat_done_93
	v_lshl_add_u32 v6, s28, 6, v101
	v_cmp_lt_u32_e64 s[68:69], s12, v179
	v_cmp_eq_u32_e32 vcc, s12, v179
	v_and_b32_e32 v0, 0xffff, v60
	v_mbcnt_lo_u32_b32 v7, s68, 0
	v_mbcnt_hi_u32_b32 v7, s69, v7
	v_add_lshl_u32 v0, v0, v7, 1
	v_cndmask_b32_e64 v0, v76, v0, s[68:69]
	ds_write_b16 v0, v6 offset:8192
	s_cbranch_vccz .Ltk_noeq_134
	s_cmp_eq_u32 s12, 0
	s_cbranch_scc1 .Ltk_noeq_134
	v_mbcnt_lo_u32_b32 v8, vcc_lo, 0
	v_mbcnt_hi_u32_b32 v8, vcc_hi, v8
	v_lshrrev_b32_e32 v1, 16, v60
	v_add3_u32 v1, v1, v8, s48
	v_cmp_gt_u32_e64 s[72:73], s84, v1
	v_lshlrev_b32_e32 v1, 1, v1
	s_and_b64 s[72:73], s[72:73], vcc
	s_nop 0
	v_cndmask_b32_e64 v1, v76, v1, s[72:73]
	ds_write_b16 v1, v6 offset:8192
; DI void topk_job(const Params& p, int b, int t0, char* lds) {
;     ...
;   const unsigned long long lt = (1ull << lane) - 1ull;
; #pragma unroll
;   for (int i = 0; i < 17; ++i) {
;     const int c = 1 + w + 8 * i;
;     if (c <= cmax) {
;       const int key = c * 64 + lane;
; #pragma unroll
;       for (int q = 0; q < 4; ++q) {
;         u16* out = p.IDX + (size_t)(b * PP + t0 + q) * 256;
;         const bool gt = sc[i][q] > T[q];
;         const bool eq = (sc[i][q] == T[q]) && (T[q] != 0u);
;         const unsigned long long m1 = __ballot(gt), m2 = __ballot(eq);
;         if ((m1 | m2) != 0ull) {
;           const unsigned bb = baseb[q * 132 + c];
;           if (gt) out[(int)(bb & 0xffffu) + __popcll(m1 & lt)] = (u16)key;
;           if (eq) { const int pos = ng[q] + (int)(bb >> 16) + __popcll(m2 & lt); if (pos < 256) out[pos] = (u16)key; }
;         }
;       }
;     }
;   }
.Ltk_noeq_134:
	v_cmp_lt_u32_e64 s[68:69], s13, v163
	v_cmp_eq_u32_e32 vcc, s13, v163
	v_and_b32_e32 v0, 0xffff, v61
	v_mbcnt_lo_u32_b32 v7, s68, 0
	v_mbcnt_hi_u32_b32 v7, s69, v7
	v_add_lshl_u32 v0, v0, v7, 1
	v_cndmask_b32_e64 v0, v76, v0, s[68:69]
	ds_write_b16 v0, v6 offset:8704
	s_cbranch_vccz .Ltk_noeq_135
	s_cmp_eq_u32 s13, 0
	s_cbranch_scc1 .Ltk_noeq_135
	v_mbcnt_lo_u32_b32 v8, vcc_lo, 0
	v_mbcnt_hi_u32_b32 v8, vcc_hi, v8
	v_lshrrev_b32_e32 v1, 16, v61
	v_add3_u32 v1, v1, v8, s49
	v_cmp_gt_u32_e64 s[72:73], s84, v1
	v_lshlrev_b32_e32 v1, 1, v1
	s_and_b64 s[72:73], s[72:73], vcc
	s_nop 0
	v_cndmask_b32_e64 v1, v76, v1, s[72:73]
	ds_write_b16 v1, v6 offset:8704
.Ltk_noeq_135:
	v_cmp_lt_u32_e64 s[68:69], s14, v142
	v_cmp_eq_u32_e32 vcc, s14, v142
	v_and_b32_e32 v0, 0xffff, v62
	v_mbcnt_lo_u32_b32 v7, s68, 0
	v_mbcnt_hi_u32_b32 v7, s69, v7
	v_add_lshl_u32 v0, v0, v7, 1
	v_cndmask_b32_e64 v0, v76, v0, s[68:69]
	ds_write_b16 v0, v6 offset:9216
	s_cbranch_vccz .Ltk_noeq_136
	s_cmp_eq_u32 s14, 0
	s_cbranch_scc1 .Ltk_noeq_136
	v_mbcnt_lo_u32_b32 v8, vcc_lo, 0
	v_mbcnt_hi_u32_b32 v8, vcc_hi, v8
	v_lshrrev_b32_e32 v1, 16, v62
	v_add3_u32 v1, v1, v8, s50
	v_cmp_gt_u32_e64 s[72:73], s84, v1
	v_lshlrev_b32_e32 v1, 1, v1
	s_and_b64 s[72:73], s[72:73], vcc
	s_nop 0
	v_cndmask_b32_e64 v1, v76, v1, s[72:73]
	ds_write_b16 v1, v6 offset:9216
.Ltk_noeq_136:
	v_cmp_lt_u32_e64 s[68:69], s15, v113
	v_cmp_eq_u32_e32 vcc, s15, v113
	v_and_b32_e32 v0, 0xffff, v63
	v_mbcnt_lo_u32_b32 v7, s68, 0
	v_mbcnt_hi_u32_b32 v7, s69, v7
	v_add_lshl_u32 v0, v0, v7, 1
	v_cndmask_b32_e64 v0, v76, v0, s[68:69]
	ds_write_b16 v0, v6 offset:9728
	s_cbranch_vccz .Ltk_noeq_137
	s_cmp_eq_u32 s15, 0
	s_cbranch_scc1 .Ltk_noeq_137
	v_mbcnt_lo_u32_b32 v8, vcc_lo, 0
	v_mbcnt_hi_u32_b32 v8, vcc_hi, v8
	v_lshrrev_b32_e32 v1, 16, v63
	v_add3_u32 v1, v1, v8, s51
	v_cmp_gt_u32_e64 s[72:73], s84, v1
	v_lshlrev_b32_e32 v1, 1, v1
	s_and_b64 s[72:73], s[72:73], vcc
	s_nop 0
	v_cndmask_b32_e64 v1, v76, v1, s[72:73]
	ds_write_b16 v1, v6 offset:9728
.Ltk_noeq_137:
	s_add_i32 s28, s28, 8
	s_cmp_gt_u32 s28, s3
	s_cbranch_scc1 .Ltk_scat_done_93
	v_lshl_add_u32 v6, s28, 6, v101
	v_cmp_lt_u32_e64 s[68:69], s12, v178
	v_cmp_eq_u32_e32 vcc, s12, v178
	v_and_b32_e32 v0, 0xffff, v64
	v_mbcnt_lo_u32_b32 v7, s68, 0
	v_mbcnt_hi_u32_b32 v7, s69, v7
	v_add_lshl_u32 v0, v0, v7, 1
	v_cndmask_b32_e64 v0, v76, v0, s[68:69]
	ds_write_b16 v0, v6 offset:8192
	s_cbranch_vccz .Ltk_noeq_138
	s_cmp_eq_u32 s12, 0
	s_cbranch_scc1 .Ltk_noeq_138
	v_mbcnt_lo_u32_b32 v8, vcc_lo, 0
	v_mbcnt_hi_u32_b32 v8, vcc_hi, v8
	v_lshrrev_b32_e32 v1, 16, v64
	v_add3_u32 v1, v1, v8, s48
	v_cmp_gt_u32_e64 s[72:73], s84, v1
	v_lshlrev_b32_e32 v1, 1, v1
	s_and_b64 s[72:73], s[72:73], vcc
	s_nop 0
	v_cndmask_b32_e64 v1, v76, v1, s[72:73]
	ds_write_b16 v1, v6 offset:8192
.Ltk_noeq_138:
	v_cmp_lt_u32_e64 s[68:69], s13, v162
	v_cmp_eq_u32_e32 vcc, s13, v162
	v_and_b32_e32 v0, 0xffff, v65
	v_mbcnt_lo_u32_b32 v7, s68, 0
	v_mbcnt_hi_u32_b32 v7, s69, v7
	v_add_lshl_u32 v0, v0, v7, 1
	v_cndmask_b32_e64 v0, v76, v0, s[68:69]
	ds_write_b16 v0, v6 offset:8704
	s_cbranch_vccz .Ltk_noeq_139
	s_cmp_eq_u32 s13, 0
	s_cbranch_scc1 .Ltk_noeq_139
	v_mbcnt_lo_u32_b32 v8, vcc_lo, 0
	v_mbcnt_hi_u32_b32 v8, vcc_hi, v8
	v_lshrrev_b32_e32 v1, 16, v65
	v_add3_u32 v1, v1, v8, s49
	v_cmp_gt_u32_e64 s[72:73], s84, v1
	v_lshlrev_b32_e32 v1, 1, v1
	s_and_b64 s[72:73], s[72:73], vcc
	s_nop 0
	v_cndmask_b32_e64 v1, v76, v1, s[72:73]
	ds_write_b16 v1, v6 offset:8704
.Ltk_noeq_139:
	v_cmp_lt_u32_e64 s[68:69], s14, v141
	v_cmp_eq_u32_e32 vcc, s14, v141
	v_and_b32_e32 v0, 0xffff, v66
	v_mbcnt_lo_u32_b32 v7, s68, 0
	v_mbcnt_hi_u32_b32 v7, s69, v7
	v_add_lshl_u32 v0, v0, v7, 1
	v_cndmask_b32_e64 v0, v76, v0, s[68:69]
	ds_write_b16 v0, v6 offset:9216
	s_cbranch_vccz .Ltk_noeq_140
	s_cmp_eq_u32 s14, 0
	s_cbranch_scc1 .Ltk_noeq_140
	v_mbcnt_lo_u32_b32 v8, vcc_lo, 0
	v_mbcnt_hi_u32_b32 v8, vcc_hi, v8
	v_lshrrev_b32_e32 v1, 16, v66
	v_add3_u32 v1, v1, v8, s50
	v_cmp_gt_u32_e64 s[72:73], s84, v1
	v_lshlrev_b32_e32 v1, 1, v1
	s_and_b64 s[72:73], s[72:73], vcc
	s_nop 0
	v_cndmask_b32_e64 v1, v76, v1, s[72:73]
	ds_write_b16 v1, v6 offset:9216
.Ltk_noeq_140:
	v_cmp_lt_u32_e64 s[68:69], s15, v111
	v_cmp_eq_u32_e32 vcc, s15, v111
	v_and_b32_e32 v0, 0xffff, v77
	v_mbcnt_lo_u32_b32 v7, s68, 0
	v_mbcnt_hi_u32_b32 v7, s69, v7
	v_add_lshl_u32 v0, v0, v7, 1
	v_cndmask_b32_e64 v0, v76, v0, s[68:69]
	ds_write_b16 v0, v6 offset:9728
	s_cbranch_vccz .Ltk_noeq_141
	s_cmp_eq_u32 s15, 0
	s_cbranch_scc1 .Ltk_noeq_141
	v_mbcnt_lo_u32_b32 v8, vcc_lo, 0
	v_mbcnt_hi_u32_b32 v8, vcc_hi, v8
	v_lshrrev_b32_e32 v1, 16, v77
	v_add3_u32 v1, v1, v8, s51
	v_cmp_gt_u32_e64 s[72:73], s84, v1
	v_lshlrev_b32_e32 v1, 1, v1
	s_and_b64 s[72:73], s[72:73], vcc
	s_nop 0
	v_cndmask_b32_e64 v1, v76, v1, s[72:73]
	ds_write_b16 v1, v6 offset:9728
.Ltk_noeq_141:
	s_add_i32 s28, s28, 8
	s_cmp_gt_u32 s28, s3
	s_cbranch_scc1 .Ltk_scat_done_93
	v_lshl_add_u32 v6, s28, 6, v101
	v_cmp_lt_u32_e64 s[68:69], s12, v177
	v_cmp_eq_u32_e32 vcc, s12, v177
	v_and_b32_e32 v0, 0xffff, v78
	v_mbcnt_lo_u32_b32 v7, s68, 0
	v_mbcnt_hi_u32_b32 v7, s69, v7
	v_add_lshl_u32 v0, v0, v7, 1
	v_cndmask_b32_e64 v0, v76, v0, s[68:69]
	ds_write_b16 v0, v6 offset:8192
	s_cbranch_vccz .Ltk_noeq_142
	s_cmp_eq_u32 s12, 0
	s_cbranch_scc1 .Ltk_noeq_142
	v_mbcnt_lo_u32_b32 v8, vcc_lo, 0
	v_mbcnt_hi_u32_b32 v8, vcc_hi, v8
	v_lshrrev_b32_e32 v1, 16, v78
	v_add3_u32 v1, v1, v8, s48
	v_cmp_gt_u32_e64 s[72:73], s84, v1
	v_lshlrev_b32_e32 v1, 1, v1
	s_and_b64 s[72:73], s[72:73], vcc
	s_nop 0
	v_cndmask_b32_e64 v1, v76, v1, s[72:73]
	ds_write_b16 v1, v6 offset:8192
; DI void topk_job(const Params& p, int b, int t0, char* lds) {
;     ...
;   const unsigned long long lt = (1ull << lane) - 1ull;
; #pragma unroll
;   for (int i = 0; i < 17; ++i) {
;     const int c = 1 + w + 8 * i;
;     if (c <= cmax) {
;       const int key = c * 64 + lane;
; #pragma unroll
;       for (int q = 0; q < 4; ++q) {
;         u16* out = p.IDX + (size_t)(b * PP + t0 + q) * 256;
;         const bool gt = sc[i][q] > T[q];
;         const bool eq = (sc[i][q] == T[q]) && (T[q] != 0u);
;         const unsigned long long m1 = __ballot(gt), m2 = __ballot(eq);
;         if ((m1 | m2) != 0ull) {
;           const unsigned bb = baseb[q * 132 + c];
;           if (gt) out[(int)(bb & 0xffffu) + __popcll(m1 & lt)] = (u16)key;
;           if (eq) { const int pos = ng[q] + (int)(bb >> 16) + __popcll(m2 & lt); if (pos < 256) out[pos] = (u16)key; }
;         }
;       }
;     }
;   }
.Ltk_noeq_142:
	v_cmp_lt_u32_e64 s[68:69], s13, v160
	v_cmp_eq_u32_e32 vcc, s13, v160
	v_and_b32_e32 v0, 0xffff, v79
	v_mbcnt_lo_u32_b32 v7, s68, 0
	v_mbcnt_hi_u32_b32 v7, s69, v7
	v_add_lshl_u32 v0, v0, v7, 1
	v_cndmask_b32_e64 v0, v76, v0, s[68:69]
	ds_write_b16 v0, v6 offset:8704
	s_cbranch_vccz .Ltk_noeq_143
	s_cmp_eq_u32 s13, 0
	s_cbranch_scc1 .Ltk_noeq_143
	v_mbcnt_lo_u32_b32 v8, vcc_lo, 0
	v_mbcnt_hi_u32_b32 v8, vcc_hi, v8
	v_lshrrev_b32_e32 v1, 16, v79
	v_add3_u32 v1, v1, v8, s49
	v_cmp_gt_u32_e64 s[72:73], s84, v1
	v_lshlrev_b32_e32 v1, 1, v1
	s_and_b64 s[72:73], s[72:73], vcc
	s_nop 0
	v_cndmask_b32_e64 v1, v76, v1, s[72:73]
	ds_write_b16 v1, v6 offset:8704
.Ltk_noeq_143:
	v_cmp_lt_u32_e64 s[68:69], s14, v140
	v_cmp_eq_u32_e32 vcc, s14, v140
	v_and_b32_e32 v0, 0xffff, v80
	v_mbcnt_lo_u32_b32 v7, s68, 0
	v_mbcnt_hi_u32_b32 v7, s69, v7
	v_add_lshl_u32 v0, v0, v7, 1
	v_cndmask_b32_e64 v0, v76, v0, s[68:69]
	ds_write_b16 v0, v6 offset:9216
	s_cbranch_vccz .Ltk_noeq_144
	s_cmp_eq_u32 s14, 0
	s_cbranch_scc1 .Ltk_noeq_144
	v_mbcnt_lo_u32_b32 v8, vcc_lo, 0
	v_mbcnt_hi_u32_b32 v8, vcc_hi, v8
	v_lshrrev_b32_e32 v1, 16, v80
	v_add3_u32 v1, v1, v8, s50
	v_cmp_gt_u32_e64 s[72:73], s84, v1
	v_lshlrev_b32_e32 v1, 1, v1
	s_and_b64 s[72:73], s[72:73], vcc
	s_nop 0
	v_cndmask_b32_e64 v1, v76, v1, s[72:73]
	ds_write_b16 v1, v6 offset:9216
.Ltk_noeq_144:
	v_cmp_lt_u32_e64 s[68:69], s15, v109
	v_cmp_eq_u32_e32 vcc, s15, v109
	v_and_b32_e32 v0, 0xffff, v81
	v_mbcnt_lo_u32_b32 v7, s68, 0
	v_mbcnt_hi_u32_b32 v7, s69, v7
	v_add_lshl_u32 v0, v0, v7, 1
	v_cndmask_b32_e64 v0, v76, v0, s[68:69]
	ds_write_b16 v0, v6 offset:9728
	s_cbranch_vccz .Ltk_noeq_145
	s_cmp_eq_u32 s15, 0
	s_cbranch_scc1 .Ltk_noeq_145
	v_mbcnt_lo_u32_b32 v8, vcc_lo, 0
	v_mbcnt_hi_u32_b32 v8, vcc_hi, v8
	v_lshrrev_b32_e32 v1, 16, v81
	v_add3_u32 v1, v1, v8, s51
	v_cmp_gt_u32_e64 s[72:73], s84, v1
	v_lshlrev_b32_e32 v1, 1, v1
	s_and_b64 s[72:73], s[72:73], vcc
	s_nop 0
	v_cndmask_b32_e64 v1, v76, v1, s[72:73]
	ds_write_b16 v1, v6 offset:9728
.Ltk_noeq_145:
	s_add_i32 s28, s28, 8
	s_cmp_gt_u32 s28, s3
	s_cbranch_scc1 .Ltk_scat_done_93
	v_lshl_add_u32 v6, s28, 6, v101
	v_cmp_lt_u32_e64 s[68:69], s12, v176
	v_cmp_eq_u32_e32 vcc, s12, v176
	v_and_b32_e32 v0, 0xffff, v82
	v_mbcnt_lo_u32_b32 v7, s68, 0
	v_mbcnt_hi_u32_b32 v7, s69, v7
	v_add_lshl_u32 v0, v0, v7, 1
	v_cndmask_b32_e64 v0, v76, v0, s[68:69]
	ds_write_b16 v0, v6 offset:8192
	s_cbranch_vccz .Ltk_noeq_146
	s_cmp_eq_u32 s12, 0
	s_cbranch_scc1 .Ltk_noeq_146
	v_mbcnt_lo_u32_b32 v8, vcc_lo, 0
	v_mbcnt_hi_u32_b32 v8, vcc_hi, v8
	v_lshrrev_b32_e32 v1, 16, v82
	v_add3_u32 v1, v1, v8, s48
	v_cmp_gt_u32_e64 s[72:73], s84, v1
	v_lshlrev_b32_e32 v1, 1, v1
	s_and_b64 s[72:73], s[72:73], vcc
	s_nop 0
	v_cndmask_b32_e64 v1, v76, v1, s[72:73]
	ds_write_b16 v1, v6 offset:8192
.Ltk_noeq_146:
	v_cmp_lt_u32_e64 s[68:69], s13, v151
	v_cmp_eq_u32_e32 vcc, s13, v151
	v_and_b32_e32 v0, 0xffff, v83
	v_mbcnt_lo_u32_b32 v7, s68, 0
	v_mbcnt_hi_u32_b32 v7, s69, v7
	v_add_lshl_u32 v0, v0, v7, 1
	v_cndmask_b32_e64 v0, v76, v0, s[68:69]
	ds_write_b16 v0, v6 offset:8704
	s_cbranch_vccz .Ltk_noeq_147
	s_cmp_eq_u32 s13, 0
	s_cbranch_scc1 .Ltk_noeq_147
	v_mbcnt_lo_u32_b32 v8, vcc_lo, 0
	v_mbcnt_hi_u32_b32 v8, vcc_hi, v8
	v_lshrrev_b32_e32 v1, 16, v83
	v_add3_u32 v1, v1, v8, s49
	v_cmp_gt_u32_e64 s[72:73], s84, v1
	v_lshlrev_b32_e32 v1, 1, v1
	s_and_b64 s[72:73], s[72:73], vcc
	s_nop 0
	v_cndmask_b32_e64 v1, v76, v1, s[72:73]
	ds_write_b16 v1, v6 offset:8704
.Ltk_noeq_147:
	v_cmp_lt_u32_e64 s[68:69], s14, v139
	v_cmp_eq_u32_e32 vcc, s14, v139
	v_and_b32_e32 v0, 0xffff, v120
	v_mbcnt_lo_u32_b32 v7, s68, 0
	v_mbcnt_hi_u32_b32 v7, s69, v7
	v_add_lshl_u32 v0, v0, v7, 1
	v_cndmask_b32_e64 v0, v76, v0, s[68:69]
	ds_write_b16 v0, v6 offset:9216
	s_cbranch_vccz .Ltk_noeq_148
	s_cmp_eq_u32 s14, 0
	s_cbranch_scc1 .Ltk_noeq_148
	v_mbcnt_lo_u32_b32 v8, vcc_lo, 0
	v_mbcnt_hi_u32_b32 v8, vcc_hi, v8
	v_lshrrev_b32_e32 v1, 16, v120
	v_add3_u32 v1, v1, v8, s50
	v_cmp_gt_u32_e64 s[72:73], s84, v1
	v_lshlrev_b32_e32 v1, 1, v1
	s_and_b64 s[72:73], s[72:73], vcc
	s_nop 0
	v_cndmask_b32_e64 v1, v76, v1, s[72:73]
	ds_write_b16 v1, v6 offset:9216
.Ltk_noeq_148:
	v_cmp_lt_u32_e64 s[68:69], s15, v107
	v_cmp_eq_u32_e32 vcc, s15, v107
	v_and_b32_e32 v0, 0xffff, v122
	v_mbcnt_lo_u32_b32 v7, s68, 0
	v_mbcnt_hi_u32_b32 v7, s69, v7
	v_add_lshl_u32 v0, v0, v7, 1
	v_cndmask_b32_e64 v0, v76, v0, s[68:69]
	ds_write_b16 v0, v6 offset:9728
	s_cbranch_vccz .Ltk_noeq_149
	s_cmp_eq_u32 s15, 0
	s_cbranch_scc1 .Ltk_noeq_149
	v_mbcnt_lo_u32_b32 v8, vcc_lo, 0
	v_mbcnt_hi_u32_b32 v8, vcc_hi, v8
	v_lshrrev_b32_e32 v1, 16, v122
	v_add3_u32 v1, v1, v8, s51
	v_cmp_gt_u32_e64 s[72:73], s84, v1
	v_lshlrev_b32_e32 v1, 1, v1
	s_and_b64 s[72:73], s[72:73], vcc
	s_nop 0
	v_cndmask_b32_e64 v1, v76, v1, s[72:73]
	ds_write_b16 v1, v6 offset:9728
.Ltk_noeq_149:
	s_add_i32 s28, s28, 8
	s_cmp_gt_u32 s28, s3
	s_cbranch_scc1 .Ltk_scat_done_93
	v_lshl_add_u32 v6, s28, 6, v101
	v_cmp_lt_u32_e64 s[68:69], s12, v174
	v_cmp_eq_u32_e32 vcc, s12, v174
	v_and_b32_e32 v0, 0xffff, v124
	v_mbcnt_lo_u32_b32 v7, s68, 0
	v_mbcnt_hi_u32_b32 v7, s69, v7
	v_add_lshl_u32 v0, v0, v7, 1
	v_cndmask_b32_e64 v0, v76, v0, s[68:69]
	ds_write_b16 v0, v6 offset:8192
	s_cbranch_vccz .Ltk_noeq_150
	s_cmp_eq_u32 s12, 0
	s_cbranch_scc1 .Ltk_noeq_150
	v_mbcnt_lo_u32_b32 v8, vcc_lo, 0
	v_mbcnt_hi_u32_b32 v8, vcc_hi, v8
	v_lshrrev_b32_e32 v1, 16, v124
	v_add3_u32 v1, v1, v8, s48
	v_cmp_gt_u32_e64 s[72:73], s84, v1
	v_lshlrev_b32_e32 v1, 1, v1
	s_and_b64 s[72:73], s[72:73], vcc
	s_nop 0
	v_cndmask_b32_e64 v1, v76, v1, s[72:73]
	ds_write_b16 v1, v6 offset:8192
; DI void topk_job(const Params& p, int b, int t0, char* lds) {
;     ...
;   const unsigned long long lt = (1ull << lane) - 1ull;
; #pragma unroll
;   for (int i = 0; i < 17; ++i) {
;     const int c = 1 + w + 8 * i;
;     if (c <= cmax) {
;       const int key = c * 64 + lane;
; #pragma unroll
;       for (int q = 0; q < 4; ++q) {
;         u16* out = p.IDX + (size_t)(b * PP + t0 + q) * 256;
;         const bool gt = sc[i][q] > T[q];
;         const bool eq = (sc[i][q] == T[q]) && (T[q] != 0u);
;         const unsigned long long m1 = __ballot(gt), m2 = __ballot(eq);
;         if ((m1 | m2) != 0ull) {
;           const unsigned bb = baseb[q * 132 + c];
;           if (gt) out[(int)(bb & 0xffffu) + __popcll(m1 & lt)] = (u16)key;
;           if (eq) { const int pos = ng[q] + (int)(bb >> 16) + __popcll(m2 & lt); if (pos < 256) out[pos] = (u16)key; }
;         }
;       }
;     }
;   }
.Ltk_noeq_150:
	v_cmp_lt_u32_e64 s[68:69], s13, v148
	v_cmp_eq_u32_e32 vcc, s13, v148
	v_and_b32_e32 v0, 0xffff, v126
	v_mbcnt_lo_u32_b32 v7, s68, 0
	v_mbcnt_hi_u32_b32 v7, s69, v7
	v_add_lshl_u32 v0, v0, v7, 1
	v_cndmask_b32_e64 v0, v76, v0, s[68:69]
	ds_write_b16 v0, v6 offset:8704
	s_cbranch_vccz .Ltk_noeq_151
	s_cmp_eq_u32 s13, 0
	s_cbranch_scc1 .Ltk_noeq_151
	v_mbcnt_lo_u32_b32 v8, vcc_lo, 0
	v_mbcnt_hi_u32_b32 v8, vcc_hi, v8
	v_lshrrev_b32_e32 v1, 16, v126
	v_add3_u32 v1, v1, v8, s49
	v_cmp_gt_u32_e64 s[72:73], s84, v1
	v_lshlrev_b32_e32 v1, 1, v1
	s_and_b64 s[72:73], s[72:73], vcc
	s_nop 0
	v_cndmask_b32_e64 v1, v76, v1, s[72:73]
	ds_write_b16 v1, v6 offset:8704
.Ltk_noeq_151:
	v_cmp_lt_u32_e64 s[68:69], s14, v131
	v_cmp_eq_u32_e32 vcc, s14, v131
	v_and_b32_e32 v0, 0xffff, v128
	v_mbcnt_lo_u32_b32 v7, s68, 0
	v_mbcnt_hi_u32_b32 v7, s69, v7
	v_add_lshl_u32 v0, v0, v7, 1
	v_cndmask_b32_e64 v0, v76, v0, s[68:69]
	ds_write_b16 v0, v6 offset:9216
	s_cbranch_vccz .Ltk_noeq_152
	s_cmp_eq_u32 s14, 0
	s_cbranch_scc1 .Ltk_noeq_152
	v_mbcnt_lo_u32_b32 v8, vcc_lo, 0
	v_mbcnt_hi_u32_b32 v8, vcc_hi, v8
	v_lshrrev_b32_e32 v1, 16, v128
	v_add3_u32 v1, v1, v8, s50
	v_cmp_gt_u32_e64 s[72:73], s84, v1
	v_lshlrev_b32_e32 v1, 1, v1
	s_and_b64 s[72:73], s[72:73], vcc
	s_nop 0
	v_cndmask_b32_e64 v1, v76, v1, s[72:73]
	ds_write_b16 v1, v6 offset:9216
.Ltk_noeq_152:
	v_cmp_lt_u32_e64 s[68:69], s15, v105
	v_cmp_eq_u32_e32 vcc, s15, v105
	v_and_b32_e32 v0, 0xffff, v130
	v_mbcnt_lo_u32_b32 v7, s68, 0
	v_mbcnt_hi_u32_b32 v7, s69, v7
	v_add_lshl_u32 v0, v0, v7, 1
	v_cndmask_b32_e64 v0, v76, v0, s[68:69]
	ds_write_b16 v0, v6 offset:9728
	s_cbranch_vccz .Ltk_noeq_153
	s_cmp_eq_u32 s15, 0
	s_cbranch_scc1 .Ltk_noeq_153
	v_mbcnt_lo_u32_b32 v8, vcc_lo, 0
	v_mbcnt_hi_u32_b32 v8, vcc_hi, v8
	v_lshrrev_b32_e32 v1, 16, v130
	v_add3_u32 v1, v1, v8, s51
	v_cmp_gt_u32_e64 s[72:73], s84, v1
	v_lshlrev_b32_e32 v1, 1, v1
	s_and_b64 s[72:73], s[72:73], vcc
	s_nop 0
	v_cndmask_b32_e64 v1, v76, v1, s[72:73]
	ds_write_b16 v1, v6 offset:9728
.Ltk_noeq_153:
	s_add_i32 s28, s28, 8
	s_cmp_gt_u32 s28, s3
	s_cbranch_scc1 .Ltk_scat_done_93
	v_lshl_add_u32 v6, s28, 6, v101
	v_cmp_lt_u32_e64 s[68:69], s12, v169
	v_cmp_eq_u32_e32 vcc, s12, v169
	v_and_b32_e32 v0, 0xffff, v132
	v_mbcnt_lo_u32_b32 v7, s68, 0
	v_mbcnt_hi_u32_b32 v7, s69, v7
	v_add_lshl_u32 v0, v0, v7, 1
	v_cndmask_b32_e64 v0, v76, v0, s[68:69]
	ds_write_b16 v0, v6 offset:8192
	s_cbranch_vccz .Ltk_noeq_154
	s_cmp_eq_u32 s12, 0
	s_cbranch_scc1 .Ltk_noeq_154
	v_mbcnt_lo_u32_b32 v8, vcc_lo, 0
	v_mbcnt_hi_u32_b32 v8, vcc_hi, v8
	v_lshrrev_b32_e32 v1, 16, v132
	v_add3_u32 v1, v1, v8, s48
	v_cmp_gt_u32_e64 s[72:73], s84, v1
	v_lshlrev_b32_e32 v1, 1, v1
	s_and_b64 s[72:73], s[72:73], vcc
	s_nop 0
	v_cndmask_b32_e64 v1, v76, v1, s[72:73]
	ds_write_b16 v1, v6 offset:8192
.Ltk_noeq_154:
	v_cmp_lt_u32_e64 s[68:69], s13, v144
	v_cmp_eq_u32_e32 vcc, s13, v144
	v_and_b32_e32 v0, 0xffff, v134
	v_mbcnt_lo_u32_b32 v7, s68, 0
	v_mbcnt_hi_u32_b32 v7, s69, v7
	v_add_lshl_u32 v0, v0, v7, 1
	v_cndmask_b32_e64 v0, v76, v0, s[68:69]
	ds_write_b16 v0, v6 offset:8704
	s_cbranch_vccz .Ltk_noeq_155
	s_cmp_eq_u32 s13, 0
	s_cbranch_scc1 .Ltk_noeq_155
	v_mbcnt_lo_u32_b32 v8, vcc_lo, 0
	v_mbcnt_hi_u32_b32 v8, vcc_hi, v8
	v_lshrrev_b32_e32 v1, 16, v134
	v_add3_u32 v1, v1, v8, s49
	v_cmp_gt_u32_e64 s[72:73], s84, v1
	v_lshlrev_b32_e32 v1, 1, v1
	s_and_b64 s[72:73], s[72:73], vcc
	s_nop 0
	v_cndmask_b32_e64 v1, v76, v1, s[72:73]
	ds_write_b16 v1, v6 offset:8704
; DI void topk_job(const Params& p, int b, int t0, char* lds) {
;     ...
;   const unsigned long long lt = (1ull << lane) - 1ull;
; #pragma unroll
;   for (int i = 0; i < 17; ++i) {
;     const int c = 1 + w + 8 * i;
;     if (c <= cmax) {
;       const int key = c * 64 + lane;
; #pragma unroll
;       for (int q = 0; q < 4; ++q) {
;         u16* out = p.IDX + (size_t)(b * PP + t0 + q) * 256;
;         const bool gt = sc[i][q] > T[q];
;         const bool eq = (sc[i][q] == T[q]) && (T[q] != 0u);
;         const unsigned long long m1 = __ballot(gt), m2 = __ballot(eq);
;         if ((m1 | m2) != 0ull) {
;           const unsigned bb = baseb[q * 132 + c];
;           if (gt) out[(int)(bb & 0xffffu) + __popcll(m1 & lt)] = (u16)key;
;           if (eq) { const int pos = ng[q] + (int)(bb >> 16) + __popcll(m2 & lt); if (pos < 256) out[pos] = (u16)key; }
;         }
;       }
;     }
;   }
.Ltk_noeq_155:
	v_cmp_lt_u32_e64 s[68:69], s14, v117
	v_cmp_eq_u32_e32 vcc, s14, v117
	v_and_b32_e32 v0, 0xffff, v137
	v_mbcnt_lo_u32_b32 v7, s68, 0
	v_mbcnt_hi_u32_b32 v7, s69, v7
	v_add_lshl_u32 v0, v0, v7, 1
	v_cndmask_b32_e64 v0, v76, v0, s[68:69]
	ds_write_b16 v0, v6 offset:9216
	s_cbranch_vccz .Ltk_noeq_156
	s_cmp_eq_u32 s14, 0
	s_cbranch_scc1 .Ltk_noeq_156
	v_mbcnt_lo_u32_b32 v8, vcc_lo, 0
	v_mbcnt_hi_u32_b32 v8, vcc_hi, v8
	v_lshrrev_b32_e32 v1, 16, v137
	v_add3_u32 v1, v1, v8, s50
	v_cmp_gt_u32_e64 s[72:73], s84, v1
	v_lshlrev_b32_e32 v1, 1, v1
	s_and_b64 s[72:73], s[72:73], vcc
	s_nop 0
	v_cndmask_b32_e64 v1, v76, v1, s[72:73]
	ds_write_b16 v1, v6 offset:9216
.Ltk_noeq_156:
	v_cmp_lt_u32_e64 s[68:69], s15, v103
	v_cmp_eq_u32_e32 vcc, s15, v103
	v_and_b32_e32 v0, 0xffff, v209
	v_mbcnt_lo_u32_b32 v7, s68, 0
	v_mbcnt_hi_u32_b32 v7, s69, v7
	v_add_lshl_u32 v0, v0, v7, 1
	v_cndmask_b32_e64 v0, v76, v0, s[68:69]
	ds_write_b16 v0, v6 offset:9728
	s_cbranch_vccz .Ltk_noeq_157
	s_cmp_eq_u32 s15, 0
	s_cbranch_scc1 .Ltk_noeq_157
	v_mbcnt_lo_u32_b32 v8, vcc_lo, 0
	v_mbcnt_hi_u32_b32 v8, vcc_hi, v8
	v_lshrrev_b32_e32 v1, 16, v209
	v_add3_u32 v1, v1, v8, s51
	v_cmp_gt_u32_e64 s[72:73], s84, v1
	v_lshlrev_b32_e32 v1, 1, v1
	s_and_b64 s[72:73], s[72:73], vcc
	s_nop 0
	v_cndmask_b32_e64 v1, v76, v1, s[72:73]
	ds_write_b16 v1, v6 offset:9728
.Ltk_noeq_157:
	s_add_i32 s28, s28, 8
	s_cmp_gt_u32 s28, s3
	s_cbranch_scc1 .Ltk_scat_done_93
	v_lshl_add_u32 v6, s28, 6, v101
	v_cmp_lt_u32_e64 s[68:69], s12, v19
	v_cmp_eq_u32_e32 vcc, s12, v19
	v_and_b32_e32 v0, 0xffff, v210
	v_mbcnt_lo_u32_b32 v7, s68, 0
	v_mbcnt_hi_u32_b32 v7, s69, v7
	v_add_lshl_u32 v0, v0, v7, 1
	v_cndmask_b32_e64 v0, v76, v0, s[68:69]
	ds_write_b16 v0, v6 offset:8192
	s_cbranch_vccz .Ltk_noeq_158
	s_cmp_eq_u32 s12, 0
	s_cbranch_scc1 .Ltk_noeq_158
	v_mbcnt_lo_u32_b32 v8, vcc_lo, 0
	v_mbcnt_hi_u32_b32 v8, vcc_hi, v8
	v_lshrrev_b32_e32 v1, 16, v210
	v_add3_u32 v1, v1, v8, s48
	v_cmp_gt_u32_e64 s[72:73], s84, v1
	v_lshlrev_b32_e32 v1, 1, v1
	s_and_b64 s[72:73], s[72:73], vcc
	s_nop 0
	v_cndmask_b32_e64 v1, v76, v1, s[72:73]
	ds_write_b16 v1, v6 offset:8192
.Ltk_noeq_158:
	v_cmp_lt_u32_e64 s[68:69], s13, v18
	v_cmp_eq_u32_e32 vcc, s13, v18
	v_and_b32_e32 v0, 0xffff, v228
	v_mbcnt_lo_u32_b32 v7, s68, 0
	v_mbcnt_hi_u32_b32 v7, s69, v7
	v_add_lshl_u32 v0, v0, v7, 1
	v_cndmask_b32_e64 v0, v76, v0, s[68:69]
	ds_write_b16 v0, v6 offset:8704
	s_cbranch_vccz .Ltk_noeq_159
	s_cmp_eq_u32 s13, 0
	s_cbranch_scc1 .Ltk_noeq_159
	v_mbcnt_lo_u32_b32 v8, vcc_lo, 0
	v_mbcnt_hi_u32_b32 v8, vcc_hi, v8
	v_lshrrev_b32_e32 v1, 16, v228
	v_add3_u32 v1, v1, v8, s49
	v_cmp_gt_u32_e64 s[72:73], s84, v1
	v_lshlrev_b32_e32 v1, 1, v1
	s_and_b64 s[72:73], s[72:73], vcc
	s_nop 0
	v_cndmask_b32_e64 v1, v76, v1, s[72:73]
	ds_write_b16 v1, v6 offset:8704
.Ltk_noeq_159:
	v_cmp_lt_u32_e64 s[68:69], s14, v17
	v_cmp_eq_u32_e32 vcc, s14, v17
	v_and_b32_e32 v0, 0xffff, v229
	v_mbcnt_lo_u32_b32 v7, s68, 0
	v_mbcnt_hi_u32_b32 v7, s69, v7
	v_add_lshl_u32 v0, v0, v7, 1
	v_cndmask_b32_e64 v0, v76, v0, s[68:69]
	ds_write_b16 v0, v6 offset:9216
	s_cbranch_vccz .Ltk_noeq_160
	s_cmp_eq_u32 s14, 0
	s_cbranch_scc1 .Ltk_noeq_160
	v_mbcnt_lo_u32_b32 v8, vcc_lo, 0
	v_mbcnt_hi_u32_b32 v8, vcc_hi, v8
	v_lshrrev_b32_e32 v1, 16, v229
	v_add3_u32 v1, v1, v8, s50
	v_cmp_gt_u32_e64 s[72:73], s84, v1
	v_lshlrev_b32_e32 v1, 1, v1
	s_and_b64 s[72:73], s[72:73], vcc
	s_nop 0
	v_cndmask_b32_e64 v1, v76, v1, s[72:73]
	ds_write_b16 v1, v6 offset:9216
.Ltk_noeq_160:
	v_cmp_lt_u32_e64 s[68:69], s15, v16
	v_cmp_eq_u32_e32 vcc, s15, v16
	v_and_b32_e32 v0, 0xffff, v230
	v_mbcnt_lo_u32_b32 v7, s68, 0
	v_mbcnt_hi_u32_b32 v7, s69, v7
	v_add_lshl_u32 v0, v0, v7, 1
	v_cndmask_b32_e64 v0, v76, v0, s[68:69]
	ds_write_b16 v0, v6 offset:9728
	s_cbranch_vccz .Ltk_noeq_161
	s_cmp_eq_u32 s15, 0
	s_cbranch_scc1 .Ltk_noeq_161
	v_mbcnt_lo_u32_b32 v8, vcc_lo, 0
	v_mbcnt_hi_u32_b32 v8, vcc_hi, v8
	v_lshrrev_b32_e32 v1, 16, v230
	v_add3_u32 v1, v1, v8, s51
	v_cmp_gt_u32_e64 s[72:73], s84, v1
	v_lshlrev_b32_e32 v1, 1, v1
	s_and_b64 s[72:73], s[72:73], vcc
	s_nop 0
	v_cndmask_b32_e64 v1, v76, v1, s[72:73]
	ds_write_b16 v1, v6 offset:9728
